# setprio immediates swapped: load segments at priority 1, MFMA segments at 0
# baseline (speedup 1.0000x reference)
.Lnb_p1:
	s_add_i32 s7, s4, 0xfff84000
	s_cmp_eq_u32 s6, 28
	s_cselect_b32 s17, s0, s7
	s_cselect_b32 s16, s1, s5
	s_or_b32 s7, s17, 0x4000
	s_mov_b32 m0, s79
	s_nop 0
	buffer_load_dwordx4 v242, s[24:27], s4 offen lds
	s_nop 0
	s_mov_b32 m0, s83
	s_nop 0
	buffer_load_dwordx4 v243, s[24:27], s4 offen lds
	s_waitcnt vmcnt(24)
	s_waitcnt lgkmcnt(0)
	s_barrier
	s_setprio 0
	s_waitcnt lgkmcnt(7)
	v_mfma_f32_16x16x32_bf16 v[180:183], v[16:19], v[192:195], 0
	v_mfma_f32_16x16x32_bf16 v[164:167], v[24:27], v[192:195], 0
	s_waitcnt lgkmcnt(5)
	v_mfma_f32_16x16x32_bf16 v[148:151], v[16:19], v[200:203], 0
	v_mfma_f32_16x16x32_bf16 v[140:143], v[24:27], v[200:203], 0
	s_waitcnt lgkmcnt(3)
	v_mfma_f32_16x16x32_bf16 v[132:135], v[16:19], v[220:223], 0
	v_mfma_f32_16x16x32_bf16 v[124:127], v[24:27], v[220:223], 0
	s_waitcnt lgkmcnt(1)
	v_mfma_f32_16x16x32_bf16 v[116:119], v[16:19], v[228:231], 0
	v_mfma_f32_16x16x32_bf16 v[108:111], v[24:27], v[228:231], 0
	v_mfma_f32_16x16x32_bf16 v[180:183], v[20:23], v[196:199], v[180:183]
	v_mfma_f32_16x16x32_bf16 v[164:167], v[28:31], v[196:199], v[164:167]
	v_mfma_f32_16x16x32_bf16 v[148:151], v[20:23], v[204:207], v[148:151]
	v_mfma_f32_16x16x32_bf16 v[140:143], v[28:31], v[204:207], v[140:143]
	v_mfma_f32_16x16x32_bf16 v[132:135], v[20:23], v[224:227], v[132:135]
	v_mfma_f32_16x16x32_bf16 v[124:127], v[28:31], v[224:227], v[124:127]
	s_waitcnt lgkmcnt(0)
	v_mfma_f32_16x16x32_bf16 v[116:119], v[20:23], v[246:249], v[116:119]
	v_mfma_f32_16x16x32_bf16 v[108:111], v[28:31], v[246:249], v[108:111]
	s_setprio 1
	s_setprio 0
	v_mfma_f32_16x16x32_bf16 v[172:175], v[152:155], v[192:195], 0
	v_mfma_f32_16x16x32_bf16 v[156:159], v[168:171], v[192:195], 0
	v_mfma_f32_16x16x32_bf16 v[144:147], v[152:155], v[200:203], 0
	v_mfma_f32_16x16x32_bf16 v[136:139], v[168:171], v[200:203], 0
	v_mfma_f32_16x16x32_bf16 v[128:131], v[152:155], v[220:223], 0
	v_mfma_f32_16x16x32_bf16 v[120:123], v[168:171], v[220:223], 0
	v_mfma_f32_16x16x32_bf16 v[112:115], v[152:155], v[228:231], 0
	v_mfma_f32_16x16x32_bf16 v[104:107], v[168:171], v[228:231], 0
	v_mfma_f32_16x16x32_bf16 v[172:175], v[160:163], v[196:199], v[172:175]
	v_mfma_f32_16x16x32_bf16 v[156:159], v[176:179], v[196:199], v[156:159]
	v_mfma_f32_16x16x32_bf16 v[144:147], v[160:163], v[204:207], v[144:147]
	v_mfma_f32_16x16x32_bf16 v[136:139], v[176:179], v[204:207], v[136:139]
	v_mfma_f32_16x16x32_bf16 v[128:131], v[160:163], v[224:227], v[128:131]
	v_mfma_f32_16x16x32_bf16 v[120:123], v[176:179], v[224:227], v[120:123]
	v_mfma_f32_16x16x32_bf16 v[112:115], v[160:163], v[246:249], v[112:115]
	v_mfma_f32_16x16x32_bf16 v[104:107], v[176:179], v[246:249], v[104:107]
	s_setprio 1
	s_barrier
	ds_read_b128 v[192:195], v245 offset:16384
	ds_read_b128 v[196:199], v245 offset:17408
	ds_read_b128 v[200:203], v245 offset:18432
	ds_read_b128 v[204:207], v245 offset:19456
	ds_read_b128 v[220:223], v245 offset:20480
	ds_read_b128 v[224:227], v245 offset:21504
	ds_read_b128 v[228:231], v245 offset:22528
	ds_read_b128 v[246:249], v245 offset:23552
	s_mov_b32 m0, s51
	s_nop 0
	buffer_load_dwordx4 v242, s[56:59], s16 offen lds
	s_add_i32 s18, s16, 0x80000
	s_mov_b32 m0, s52
	s_nop 0
	buffer_load_dwordx4 v243, s[56:59], s16 offen lds
	s_nop 0
	s_mov_b32 m0, s53
	s_nop 0
	buffer_load_dwordx4 v242, s[56:59], s18 offen lds
	s_nop 0
	s_mov_b32 m0, s55
	s_nop 0
	buffer_load_dwordx4 v243, s[56:59], s18 offen lds
	s_nop 0
	s_mov_b32 m0, s31
	s_nop 0
	buffer_load_dwordx4 v242, s[24:27], s17 offen lds
	s_nop 0
	s_mov_b32 m0, s68
	s_nop 0
	buffer_load_dwordx4 v243, s[24:27], s17 offen lds
	s_waitcnt vmcnt(24)
	s_waitcnt lgkmcnt(0)
	s_barrier
	s_setprio 0
	s_waitcnt lgkmcnt(7)
	v_mfma_f32_16x16x32_bf16 v[76:79], v[16:19], v[192:195], 0
	v_mfma_f32_16x16x32_bf16 v[68:71], v[24:27], v[192:195], 0
	s_waitcnt lgkmcnt(5)
	v_mfma_f32_16x16x32_bf16 v[60:63], v[16:19], v[200:203], 0
	v_mfma_f32_16x16x32_bf16 v[52:55], v[24:27], v[200:203], 0
	s_waitcnt lgkmcnt(3)
	v_mfma_f32_16x16x32_bf16 v[44:47], v[16:19], v[220:223], 0
	v_mfma_f32_16x16x32_bf16 v[36:39], v[24:27], v[220:223], 0
	s_waitcnt lgkmcnt(1)
	v_mfma_f32_16x16x32_bf16 v[12:15], v[16:19], v[228:231], 0
	v_mfma_f32_16x16x32_bf16 v[4:7], v[24:27], v[228:231], 0
	v_mfma_f32_16x16x32_bf16 v[76:79], v[20:23], v[196:199], v[76:79]
	v_mfma_f32_16x16x32_bf16 v[68:71], v[28:31], v[196:199], v[68:71]
	v_mfma_f32_16x16x32_bf16 v[60:63], v[20:23], v[204:207], v[60:63]
	v_mfma_f32_16x16x32_bf16 v[52:55], v[28:31], v[204:207], v[52:55]
	v_mfma_f32_16x16x32_bf16 v[44:47], v[20:23], v[224:227], v[44:47]
	v_mfma_f32_16x16x32_bf16 v[36:39], v[28:31], v[224:227], v[36:39]
	s_waitcnt lgkmcnt(0)
	v_mfma_f32_16x16x32_bf16 v[12:15], v[20:23], v[246:249], v[12:15]
	v_mfma_f32_16x16x32_bf16 v[4:7], v[28:31], v[246:249], v[4:7]
	s_setprio 1
	s_setprio 0
	v_mfma_f32_16x16x32_bf16 v[40:43], v[152:155], v[220:223], 0
	v_mfma_f32_16x16x32_bf16 v[32:35], v[168:171], v[220:223], 0
	v_mfma_f32_16x16x32_bf16 v[8:11], v[152:155], v[228:231], 0
	v_mfma_f32_16x16x32_bf16 v[0:3], v[168:171], v[228:231], 0
	v_mfma_f32_16x16x32_bf16 v[16:19], v[152:155], v[192:195], 0
	v_mfma_f32_16x16x32_bf16 v[20:23], v[168:171], v[192:195], 0
	v_mfma_f32_16x16x32_bf16 v[24:27], v[152:155], v[200:203], 0
	v_mfma_f32_16x16x32_bf16 v[28:31], v[168:171], v[200:203], 0
	v_mfma_f32_16x16x32_bf16 v[40:43], v[160:163], v[224:227], v[40:43]
	v_mfma_f32_16x16x32_bf16 v[32:35], v[176:179], v[224:227], v[32:35]
	v_mfma_f32_16x16x32_bf16 v[8:11], v[160:163], v[246:249], v[8:11]
	v_mfma_f32_16x16x32_bf16 v[0:3], v[176:179], v[246:249], v[0:3]
	v_mfma_f32_16x16x32_bf16 v[16:19], v[160:163], v[196:199], v[16:19]
	v_mfma_f32_16x16x32_bf16 v[20:23], v[176:179], v[196:199], v[20:23]
	v_mfma_f32_16x16x32_bf16 v[24:27], v[160:163], v[204:207], v[24:27]
	v_mfma_f32_16x16x32_bf16 v[28:31], v[176:179], v[204:207], v[28:31]
	s_setprio 1
	s_barrier
	v_add_u32_e32 v72, 0x18000, v83
	v_add_u32_e32 v80, 0x1c000, v83
	ds_read_b128 v[48:51], v72
	ds_read_b128 v[56:59], v72 offset:1024
	ds_read_b128 v[64:67], v72 offset:2048
	ds_read_b128 v[72:75], v72 offset:3072
	ds_read_b128 v[152:155], v80
	ds_read_b128 v[160:163], v80 offset:1024
	ds_read_b128 v[168:171], v80 offset:2048
	ds_read_b128 v[176:179], v80 offset:3072
	ds_read_b128 v[192:195], v245 offset:32768
	ds_read_b128 v[196:199], v245 offset:33792
	ds_read_b128 v[200:203], v245 offset:34816
	ds_read_b128 v[204:207], v245 offset:35840
	ds_read_b128 v[220:223], v245 offset:36864
	ds_read_b128 v[224:227], v245 offset:37888
	ds_read_b128 v[228:231], v245 offset:38912
	ds_read_b128 v[246:249], v245 offset:39936
	s_add_i32 s17, s17, 0x80000
	s_mov_b32 m0, s69
	s_nop 0
	buffer_load_dwordx4 v242, s[24:27], s17 offen lds
	s_nop 0
	s_mov_b32 m0, s70
	s_nop 0
	buffer_load_dwordx4 v243, s[24:27], s17 offen lds
	s_waitcnt vmcnt(8)
	s_waitcnt lgkmcnt(0)
	s_barrier
	s_setprio 0
	s_waitcnt lgkmcnt(7)
	v_mfma_f32_16x16x32_bf16 v[180:183], v[48:51], v[192:195], v[180:183]
	v_mfma_f32_16x16x32_bf16 v[164:167], v[64:67], v[192:195], v[164:167]
	s_waitcnt lgkmcnt(5)
	v_mfma_f32_16x16x32_bf16 v[148:151], v[48:51], v[200:203], v[148:151]
	v_mfma_f32_16x16x32_bf16 v[140:143], v[64:67], v[200:203], v[140:143]
	s_waitcnt lgkmcnt(3)
	v_mfma_f32_16x16x32_bf16 v[132:135], v[48:51], v[220:223], v[132:135]
	v_mfma_f32_16x16x32_bf16 v[124:127], v[64:67], v[220:223], v[124:127]
	s_waitcnt lgkmcnt(1)
	v_mfma_f32_16x16x32_bf16 v[116:119], v[48:51], v[228:231], v[116:119]
	v_mfma_f32_16x16x32_bf16 v[108:111], v[64:67], v[228:231], v[108:111]
	v_mfma_f32_16x16x32_bf16 v[180:183], v[56:59], v[196:199], v[180:183]
	v_mfma_f32_16x16x32_bf16 v[164:167], v[72:75], v[196:199], v[164:167]
	v_mfma_f32_16x16x32_bf16 v[148:151], v[56:59], v[204:207], v[148:151]
	v_mfma_f32_16x16x32_bf16 v[140:143], v[72:75], v[204:207], v[140:143]
	v_mfma_f32_16x16x32_bf16 v[132:135], v[56:59], v[224:227], v[132:135]
	v_mfma_f32_16x16x32_bf16 v[124:127], v[72:75], v[224:227], v[124:127]
	s_waitcnt lgkmcnt(0)
	v_mfma_f32_16x16x32_bf16 v[116:119], v[56:59], v[246:249], v[116:119]
	v_mfma_f32_16x16x32_bf16 v[108:111], v[72:75], v[246:249], v[108:111]
	s_setprio 1
	s_setprio 0
	v_mfma_f32_16x16x32_bf16 v[172:175], v[152:155], v[192:195], v[172:175]
	v_mfma_f32_16x16x32_bf16 v[156:159], v[168:171], v[192:195], v[156:159]
	v_mfma_f32_16x16x32_bf16 v[144:147], v[152:155], v[200:203], v[144:147]
	v_mfma_f32_16x16x32_bf16 v[136:139], v[168:171], v[200:203], v[136:139]
	v_mfma_f32_16x16x32_bf16 v[128:131], v[152:155], v[220:223], v[128:131]
	v_mfma_f32_16x16x32_bf16 v[120:123], v[168:171], v[220:223], v[120:123]
	v_mfma_f32_16x16x32_bf16 v[112:115], v[152:155], v[228:231], v[112:115]
	v_mfma_f32_16x16x32_bf16 v[104:107], v[168:171], v[228:231], v[104:107]
	v_mfma_f32_16x16x32_bf16 v[172:175], v[160:163], v[196:199], v[172:175]
	v_mfma_f32_16x16x32_bf16 v[156:159], v[176:179], v[196:199], v[156:159]
	v_mfma_f32_16x16x32_bf16 v[144:147], v[160:163], v[204:207], v[144:147]
	v_mfma_f32_16x16x32_bf16 v[136:139], v[176:179], v[204:207], v[136:139]
	v_mfma_f32_16x16x32_bf16 v[128:131], v[160:163], v[224:227], v[128:131]
	v_mfma_f32_16x16x32_bf16 v[120:123], v[176:179], v[224:227], v[120:123]
	v_mfma_f32_16x16x32_bf16 v[112:115], v[160:163], v[246:249], v[112:115]
	v_mfma_f32_16x16x32_bf16 v[104:107], v[176:179], v[246:249], v[104:107]
	s_setprio 1
	s_barrier
	ds_read_b128 v[192:195], v245 offset:49152
	ds_read_b128 v[196:199], v245 offset:50176
	ds_read_b128 v[200:203], v245 offset:51200
	ds_read_b128 v[204:207], v245 offset:52224
	ds_read_b128 v[220:223], v245 offset:53248
	ds_read_b128 v[224:227], v245 offset:54272
	ds_read_b128 v[228:231], v245 offset:55296
	ds_read_b128 v[246:249], v245 offset:56320
	s_or_b32 s17, s16, 0x4000
	s_mov_b32 m0, s73
	s_nop 0
	buffer_load_dwordx4 v242, s[56:59], s17 offen lds
	s_add_i32 s16, s16, 0x84000
	s_mov_b32 m0, s74
	s_nop 0
	buffer_load_dwordx4 v243, s[56:59], s17 offen lds
	s_nop 0
	s_mov_b32 m0, s77
	s_nop 0
	buffer_load_dwordx4 v242, s[56:59], s16 offen lds
	s_nop 0
	s_mov_b32 m0, s78
	s_nop 0
	buffer_load_dwordx4 v243, s[56:59], s16 offen lds
	s_nop 0
	s_mov_b32 m0, s75
	s_nop 0
	buffer_load_dwordx4 v242, s[24:27], s7 offen lds
	s_nop 0
	s_mov_b32 m0, s76
	s_nop 0
	buffer_load_dwordx4 v243, s[24:27], s7 offen lds
	s_waitcnt vmcnt(8)
	s_waitcnt lgkmcnt(0)
	s_barrier
	s_setprio 0
	s_waitcnt lgkmcnt(7)
	v_mfma_f32_16x16x32_bf16 v[76:79], v[48:51], v[192:195], v[76:79]
	v_mfma_f32_16x16x32_bf16 v[68:71], v[64:67], v[192:195], v[68:71]
	s_waitcnt lgkmcnt(5)
	v_mfma_f32_16x16x32_bf16 v[60:63], v[48:51], v[200:203], v[60:63]
	v_mfma_f32_16x16x32_bf16 v[52:55], v[64:67], v[200:203], v[52:55]
	s_waitcnt lgkmcnt(3)
	v_mfma_f32_16x16x32_bf16 v[44:47], v[48:51], v[220:223], v[44:47]
	v_mfma_f32_16x16x32_bf16 v[36:39], v[64:67], v[220:223], v[36:39]
	s_waitcnt lgkmcnt(1)
	v_mfma_f32_16x16x32_bf16 v[12:15], v[48:51], v[228:231], v[12:15]
	v_mfma_f32_16x16x32_bf16 v[4:7], v[64:67], v[228:231], v[4:7]
	v_mfma_f32_16x16x32_bf16 v[76:79], v[56:59], v[196:199], v[76:79]
	v_mfma_f32_16x16x32_bf16 v[68:71], v[72:75], v[196:199], v[68:71]
	v_mfma_f32_16x16x32_bf16 v[60:63], v[56:59], v[204:207], v[60:63]
	v_mfma_f32_16x16x32_bf16 v[52:55], v[72:75], v[204:207], v[52:55]
	v_mfma_f32_16x16x32_bf16 v[44:47], v[56:59], v[224:227], v[44:47]
	v_mfma_f32_16x16x32_bf16 v[36:39], v[72:75], v[224:227], v[36:39]
	s_waitcnt lgkmcnt(0)
	v_mfma_f32_16x16x32_bf16 v[12:15], v[56:59], v[246:249], v[12:15]
	v_mfma_f32_16x16x32_bf16 v[4:7], v[72:75], v[246:249], v[4:7]
	s_setprio 1
	s_setprio 0
	v_mfma_f32_16x16x32_bf16 v[16:19], v[152:155], v[192:195], v[16:19]
	v_mfma_f32_16x16x32_bf16 v[72:75], v[160:163], v[196:199], v[16:19]
	v_mfma_f32_16x16x32_bf16 v[16:19], v[168:171], v[192:195], v[20:23]
	v_mfma_f32_16x16x32_bf16 v[64:67], v[176:179], v[196:199], v[16:19]
	v_mfma_f32_16x16x32_bf16 v[16:19], v[152:155], v[200:203], v[24:27]
	v_mfma_f32_16x16x32_bf16 v[56:59], v[160:163], v[204:207], v[16:19]
	v_mfma_f32_16x16x32_bf16 v[16:19], v[168:171], v[200:203], v[28:31]
	v_mfma_f32_16x16x32_bf16 v[48:51], v[176:179], v[204:207], v[16:19]
	v_mfma_f32_16x16x32_bf16 v[16:19], v[152:155], v[220:223], v[40:43]
	v_mfma_f32_16x16x32_bf16 v[40:43], v[160:163], v[224:227], v[16:19]
	v_mfma_f32_16x16x32_bf16 v[16:19], v[168:171], v[220:223], v[32:35]
	v_mfma_f32_16x16x32_bf16 v[8:11], v[152:155], v[228:231], v[8:11]
	v_mfma_f32_16x16x32_bf16 v[0:3], v[168:171], v[228:231], v[0:3]
	v_mfma_f32_16x16x32_bf16 v[32:35], v[176:179], v[224:227], v[16:19]
	v_mfma_f32_16x16x32_bf16 v[8:11], v[160:163], v[246:249], v[8:11]
	v_mfma_f32_16x16x32_bf16 v[0:3], v[176:179], v[246:249], v[0:3]
	s_setprio 1
	s_barrier
	s_add_i32 s6, s6, 2
	s_add_i32 s4, s4, 0x8000
	s_add_i32 s5, s5, 0x8000
.LBB0_143:
	v_add_u32_e32 v28, 0x10000, v83
	v_add_u32_e32 v80, 0x14000, v83
	ds_read_b128 v[16:19], v28
	ds_read_b128 v[20:23], v28 offset:1024
	ds_read_b128 v[24:27], v28 offset:2048
	ds_read_b128 v[28:31], v28 offset:3072
	ds_read_b128 v[152:155], v80
	ds_read_b128 v[160:163], v80 offset:1024
	ds_read_b128 v[168:171], v80 offset:2048
	ds_read_b128 v[176:179], v80 offset:3072
	s_add_i32 s7, s4, 0xfff84000
	s_cmp_eq_u32 s6, 28
	s_cselect_b32 s17, s0, s7
	s_cselect_b32 s16, s1, s5
	s_or_b32 s7, s17, 0x4000
	ds_read_b128 v[192:195], v245
	ds_read_b128 v[196:199], v245 offset:1024
	ds_read_b128 v[200:203], v245 offset:2048
	ds_read_b128 v[204:207], v245 offset:3072
	ds_read_b128 v[220:223], v245 offset:4096
	ds_read_b128 v[224:227], v245 offset:5120
	ds_read_b128 v[228:231], v245 offset:6144
	ds_read_b128 v[246:249], v245 offset:7168
	s_mov_b32 m0, s79
	s_nop 0
	buffer_load_dwordx4 v242, s[24:27], s4 offen lds
	s_nop 0
	s_mov_b32 m0, s83
	s_nop 0
	buffer_load_dwordx4 v243, s[24:27], s4 offen lds
	s_waitcnt vmcnt(8)
	s_waitcnt lgkmcnt(0)
	s_barrier
	s_setprio 0
	s_waitcnt lgkmcnt(7)
	v_mfma_f32_16x16x32_bf16 v[180:183], v[16:19], v[192:195], v[180:183]
	v_mfma_f32_16x16x32_bf16 v[164:167], v[24:27], v[192:195], v[164:167]
	s_waitcnt lgkmcnt(5)
	v_mfma_f32_16x16x32_bf16 v[148:151], v[16:19], v[200:203], v[148:151]
	v_mfma_f32_16x16x32_bf16 v[140:143], v[24:27], v[200:203], v[140:143]
	s_waitcnt lgkmcnt(3)
	v_mfma_f32_16x16x32_bf16 v[132:135], v[16:19], v[220:223], v[132:135]
	v_mfma_f32_16x16x32_bf16 v[124:127], v[24:27], v[220:223], v[124:127]
	s_waitcnt lgkmcnt(1)
	v_mfma_f32_16x16x32_bf16 v[116:119], v[16:19], v[228:231], v[116:119]
	v_mfma_f32_16x16x32_bf16 v[108:111], v[24:27], v[228:231], v[108:111]
	v_mfma_f32_16x16x32_bf16 v[180:183], v[20:23], v[196:199], v[180:183]
	v_mfma_f32_16x16x32_bf16 v[164:167], v[28:31], v[196:199], v[164:167]
	v_mfma_f32_16x16x32_bf16 v[148:151], v[20:23], v[204:207], v[148:151]
	v_mfma_f32_16x16x32_bf16 v[140:143], v[28:31], v[204:207], v[140:143]
	v_mfma_f32_16x16x32_bf16 v[132:135], v[20:23], v[224:227], v[132:135]
	v_mfma_f32_16x16x32_bf16 v[124:127], v[28:31], v[224:227], v[124:127]
	s_waitcnt lgkmcnt(0)
	v_mfma_f32_16x16x32_bf16 v[116:119], v[20:23], v[246:249], v[116:119]
	v_mfma_f32_16x16x32_bf16 v[108:111], v[28:31], v[246:249], v[108:111]
	s_setprio 1
	s_setprio 0
	v_mfma_f32_16x16x32_bf16 v[172:175], v[152:155], v[192:195], v[172:175]
	v_mfma_f32_16x16x32_bf16 v[156:159], v[168:171], v[192:195], v[156:159]
	v_mfma_f32_16x16x32_bf16 v[144:147], v[152:155], v[200:203], v[144:147]
	v_mfma_f32_16x16x32_bf16 v[136:139], v[168:171], v[200:203], v[136:139]
	v_mfma_f32_16x16x32_bf16 v[128:131], v[152:155], v[220:223], v[128:131]
	v_mfma_f32_16x16x32_bf16 v[120:123], v[168:171], v[220:223], v[120:123]
	v_mfma_f32_16x16x32_bf16 v[112:115], v[152:155], v[228:231], v[112:115]
	v_mfma_f32_16x16x32_bf16 v[104:107], v[168:171], v[228:231], v[104:107]
	v_mfma_f32_16x16x32_bf16 v[172:175], v[160:163], v[196:199], v[172:175]
	v_mfma_f32_16x16x32_bf16 v[156:159], v[176:179], v[196:199], v[156:159]
	v_mfma_f32_16x16x32_bf16 v[144:147], v[160:163], v[204:207], v[144:147]
	v_mfma_f32_16x16x32_bf16 v[136:139], v[176:179], v[204:207], v[136:139]
	v_mfma_f32_16x16x32_bf16 v[128:131], v[160:163], v[224:227], v[128:131]
	v_mfma_f32_16x16x32_bf16 v[120:123], v[176:179], v[224:227], v[120:123]
	v_mfma_f32_16x16x32_bf16 v[112:115], v[160:163], v[246:249], v[112:115]
	v_mfma_f32_16x16x32_bf16 v[104:107], v[176:179], v[246:249], v[104:107]
	s_setprio 1
	s_barrier
	ds_read_b128 v[192:195], v245 offset:16384
	ds_read_b128 v[196:199], v245 offset:17408
	ds_read_b128 v[200:203], v245 offset:18432
	ds_read_b128 v[204:207], v245 offset:19456
	ds_read_b128 v[220:223], v245 offset:20480
	ds_read_b128 v[224:227], v245 offset:21504
	ds_read_b128 v[228:231], v245 offset:22528
	ds_read_b128 v[246:249], v245 offset:23552
	s_mov_b32 m0, s51
	s_nop 0
	buffer_load_dwordx4 v242, s[56:59], s16 offen lds
	s_add_i32 s18, s16, 0x80000
	s_mov_b32 m0, s52
	s_nop 0
	buffer_load_dwordx4 v243, s[56:59], s16 offen lds
	s_nop 0
	s_mov_b32 m0, s53
	s_nop 0
	buffer_load_dwordx4 v242, s[56:59], s18 offen lds
	s_nop 0
	s_mov_b32 m0, s55
	s_nop 0
	buffer_load_dwordx4 v243, s[56:59], s18 offen lds
	s_nop 0
	s_mov_b32 m0, s31
	s_nop 0
	buffer_load_dwordx4 v242, s[24:27], s17 offen lds
	s_nop 0
	s_mov_b32 m0, s68
	s_nop 0
	buffer_load_dwordx4 v243, s[24:27], s17 offen lds
	s_waitcnt vmcnt(8)
	s_waitcnt lgkmcnt(0)
	s_barrier
	s_setprio 0
	s_waitcnt lgkmcnt(7)
	v_mfma_f32_16x16x32_bf16 v[76:79], v[16:19], v[192:195], v[76:79]
	v_mfma_f32_16x16x32_bf16 v[68:71], v[24:27], v[192:195], v[68:71]
	s_waitcnt lgkmcnt(5)
	v_mfma_f32_16x16x32_bf16 v[60:63], v[16:19], v[200:203], v[60:63]
	v_mfma_f32_16x16x32_bf16 v[52:55], v[24:27], v[200:203], v[52:55]
	s_waitcnt lgkmcnt(3)
	v_mfma_f32_16x16x32_bf16 v[44:47], v[16:19], v[220:223], v[44:47]
	v_mfma_f32_16x16x32_bf16 v[36:39], v[24:27], v[220:223], v[36:39]
	s_waitcnt lgkmcnt(1)
	v_mfma_f32_16x16x32_bf16 v[12:15], v[16:19], v[228:231], v[12:15]
	v_mfma_f32_16x16x32_bf16 v[4:7], v[24:27], v[228:231], v[4:7]
	v_mfma_f32_16x16x32_bf16 v[76:79], v[20:23], v[196:199], v[76:79]
	v_mfma_f32_16x16x32_bf16 v[68:71], v[28:31], v[196:199], v[68:71]
	v_mfma_f32_16x16x32_bf16 v[60:63], v[20:23], v[204:207], v[60:63]
	v_mfma_f32_16x16x32_bf16 v[52:55], v[28:31], v[204:207], v[52:55]
	v_mfma_f32_16x16x32_bf16 v[44:47], v[20:23], v[224:227], v[44:47]
	v_mfma_f32_16x16x32_bf16 v[36:39], v[28:31], v[224:227], v[36:39]
	s_waitcnt lgkmcnt(0)
	v_mfma_f32_16x16x32_bf16 v[12:15], v[20:23], v[246:249], v[12:15]
	v_mfma_f32_16x16x32_bf16 v[4:7], v[28:31], v[246:249], v[4:7]
	s_setprio 1
	s_setprio 0
	v_mfma_f32_16x16x32_bf16 v[40:43], v[152:155], v[220:223], v[40:43]
	v_mfma_f32_16x16x32_bf16 v[32:35], v[168:171], v[220:223], v[32:35]
	v_mfma_f32_16x16x32_bf16 v[8:11], v[152:155], v[228:231], v[8:11]
	v_mfma_f32_16x16x32_bf16 v[0:3], v[168:171], v[228:231], v[0:3]
	v_mfma_f32_16x16x32_bf16 v[16:19], v[152:155], v[192:195], v[72:75]
	v_mfma_f32_16x16x32_bf16 v[20:23], v[168:171], v[192:195], v[64:67]
	v_mfma_f32_16x16x32_bf16 v[24:27], v[152:155], v[200:203], v[56:59]
	v_mfma_f32_16x16x32_bf16 v[28:31], v[168:171], v[200:203], v[48:51]
	v_mfma_f32_16x16x32_bf16 v[40:43], v[160:163], v[224:227], v[40:43]
	v_mfma_f32_16x16x32_bf16 v[32:35], v[176:179], v[224:227], v[32:35]
	v_mfma_f32_16x16x32_bf16 v[8:11], v[160:163], v[246:249], v[8:11]
	v_mfma_f32_16x16x32_bf16 v[0:3], v[176:179], v[246:249], v[0:3]
	v_mfma_f32_16x16x32_bf16 v[16:19], v[160:163], v[196:199], v[16:19]
	v_mfma_f32_16x16x32_bf16 v[20:23], v[176:179], v[196:199], v[20:23]
	v_mfma_f32_16x16x32_bf16 v[24:27], v[160:163], v[204:207], v[24:27]
	v_mfma_f32_16x16x32_bf16 v[28:31], v[176:179], v[204:207], v[28:31]
	s_setprio 1
	s_barrier
	v_add_u32_e32 v72, 0x18000, v83
	v_add_u32_e32 v80, 0x1c000, v83
	ds_read_b128 v[48:51], v72
	ds_read_b128 v[56:59], v72 offset:1024
	ds_read_b128 v[64:67], v72 offset:2048
	ds_read_b128 v[72:75], v72 offset:3072
	ds_read_b128 v[152:155], v80
	ds_read_b128 v[160:163], v80 offset:1024
	ds_read_b128 v[168:171], v80 offset:2048
	ds_read_b128 v[176:179], v80 offset:3072
	ds_read_b128 v[192:195], v245 offset:32768
	ds_read_b128 v[196:199], v245 offset:33792
	ds_read_b128 v[200:203], v245 offset:34816
	ds_read_b128 v[204:207], v245 offset:35840
	ds_read_b128 v[220:223], v245 offset:36864
	ds_read_b128 v[224:227], v245 offset:37888
	ds_read_b128 v[228:231], v245 offset:38912
	ds_read_b128 v[246:249], v245 offset:39936
	s_add_i32 s17, s17, 0x80000
	s_mov_b32 m0, s69
	s_nop 0
	buffer_load_dwordx4 v242, s[24:27], s17 offen lds
	s_nop 0
	s_mov_b32 m0, s70
	s_nop 0
	buffer_load_dwordx4 v243, s[24:27], s17 offen lds
	s_waitcnt vmcnt(8)
	s_waitcnt lgkmcnt(0)
	s_barrier
	s_setprio 0
	s_waitcnt lgkmcnt(7)
	v_mfma_f32_16x16x32_bf16 v[180:183], v[48:51], v[192:195], v[180:183]
	v_mfma_f32_16x16x32_bf16 v[164:167], v[64:67], v[192:195], v[164:167]
	s_waitcnt lgkmcnt(5)
	v_mfma_f32_16x16x32_bf16 v[148:151], v[48:51], v[200:203], v[148:151]
	v_mfma_f32_16x16x32_bf16 v[140:143], v[64:67], v[200:203], v[140:143]
	s_waitcnt lgkmcnt(3)
	v_mfma_f32_16x16x32_bf16 v[132:135], v[48:51], v[220:223], v[132:135]
	v_mfma_f32_16x16x32_bf16 v[124:127], v[64:67], v[220:223], v[124:127]
	s_waitcnt lgkmcnt(1)
	v_mfma_f32_16x16x32_bf16 v[116:119], v[48:51], v[228:231], v[116:119]
	v_mfma_f32_16x16x32_bf16 v[108:111], v[64:67], v[228:231], v[108:111]
	v_mfma_f32_16x16x32_bf16 v[180:183], v[56:59], v[196:199], v[180:183]
	v_mfma_f32_16x16x32_bf16 v[164:167], v[72:75], v[196:199], v[164:167]
	v_mfma_f32_16x16x32_bf16 v[148:151], v[56:59], v[204:207], v[148:151]
	v_mfma_f32_16x16x32_bf16 v[140:143], v[72:75], v[204:207], v[140:143]
	v_mfma_f32_16x16x32_bf16 v[132:135], v[56:59], v[224:227], v[132:135]
	v_mfma_f32_16x16x32_bf16 v[124:127], v[72:75], v[224:227], v[124:127]
	s_waitcnt lgkmcnt(0)
	v_mfma_f32_16x16x32_bf16 v[116:119], v[56:59], v[246:249], v[116:119]
	v_mfma_f32_16x16x32_bf16 v[108:111], v[72:75], v[246:249], v[108:111]
	s_setprio 1
	s_setprio 0
	v_mfma_f32_16x16x32_bf16 v[172:175], v[152:155], v[192:195], v[172:175]
	v_mfma_f32_16x16x32_bf16 v[156:159], v[168:171], v[192:195], v[156:159]
	v_mfma_f32_16x16x32_bf16 v[144:147], v[152:155], v[200:203], v[144:147]
	v_mfma_f32_16x16x32_bf16 v[136:139], v[168:171], v[200:203], v[136:139]
	v_mfma_f32_16x16x32_bf16 v[128:131], v[152:155], v[220:223], v[128:131]
	v_mfma_f32_16x16x32_bf16 v[120:123], v[168:171], v[220:223], v[120:123]
	v_mfma_f32_16x16x32_bf16 v[112:115], v[152:155], v[228:231], v[112:115]
	v_mfma_f32_16x16x32_bf16 v[104:107], v[168:171], v[228:231], v[104:107]
	v_mfma_f32_16x16x32_bf16 v[172:175], v[160:163], v[196:199], v[172:175]
	v_mfma_f32_16x16x32_bf16 v[156:159], v[176:179], v[196:199], v[156:159]
	v_mfma_f32_16x16x32_bf16 v[144:147], v[160:163], v[204:207], v[144:147]
	v_mfma_f32_16x16x32_bf16 v[136:139], v[176:179], v[204:207], v[136:139]
	v_mfma_f32_16x16x32_bf16 v[128:131], v[160:163], v[224:227], v[128:131]
	v_mfma_f32_16x16x32_bf16 v[120:123], v[176:179], v[224:227], v[120:123]
	v_mfma_f32_16x16x32_bf16 v[112:115], v[160:163], v[246:249], v[112:115]
	v_mfma_f32_16x16x32_bf16 v[104:107], v[176:179], v[246:249], v[104:107]
	s_setprio 1
	s_barrier
	ds_read_b128 v[192:195], v245 offset:49152
	ds_read_b128 v[196:199], v245 offset:50176
	ds_read_b128 v[200:203], v245 offset:51200
	ds_read_b128 v[204:207], v245 offset:52224
	ds_read_b128 v[220:223], v245 offset:53248
	ds_read_b128 v[224:227], v245 offset:54272
	ds_read_b128 v[228:231], v245 offset:55296
	ds_read_b128 v[246:249], v245 offset:56320
	s_or_b32 s17, s16, 0x4000
	s_mov_b32 m0, s73
	s_nop 0
	buffer_load_dwordx4 v242, s[56:59], s17 offen lds
	s_add_i32 s16, s16, 0x84000
	s_mov_b32 m0, s74
	s_nop 0
	buffer_load_dwordx4 v243, s[56:59], s17 offen lds
	s_nop 0
	s_mov_b32 m0, s77
	s_nop 0
	buffer_load_dwordx4 v242, s[56:59], s16 offen lds
	s_nop 0
	s_mov_b32 m0, s78
	s_nop 0
	buffer_load_dwordx4 v243, s[56:59], s16 offen lds
	s_nop 0
	s_mov_b32 m0, s75
	s_nop 0
	buffer_load_dwordx4 v242, s[24:27], s7 offen lds
	s_nop 0
	s_mov_b32 m0, s76
	s_nop 0
	buffer_load_dwordx4 v243, s[24:27], s7 offen lds
	s_waitcnt vmcnt(8)
	s_waitcnt lgkmcnt(0)
	s_barrier
	s_setprio 0
	s_waitcnt lgkmcnt(7)
	v_mfma_f32_16x16x32_bf16 v[76:79], v[48:51], v[192:195], v[76:79]
	v_mfma_f32_16x16x32_bf16 v[68:71], v[64:67], v[192:195], v[68:71]
	s_waitcnt lgkmcnt(5)
	v_mfma_f32_16x16x32_bf16 v[60:63], v[48:51], v[200:203], v[60:63]
	v_mfma_f32_16x16x32_bf16 v[52:55], v[64:67], v[200:203], v[52:55]
	s_waitcnt lgkmcnt(3)
	v_mfma_f32_16x16x32_bf16 v[44:47], v[48:51], v[220:223], v[44:47]
	v_mfma_f32_16x16x32_bf16 v[36:39], v[64:67], v[220:223], v[36:39]
	s_waitcnt lgkmcnt(1)
	v_mfma_f32_16x16x32_bf16 v[12:15], v[48:51], v[228:231], v[12:15]
	v_mfma_f32_16x16x32_bf16 v[4:7], v[64:67], v[228:231], v[4:7]
	v_mfma_f32_16x16x32_bf16 v[76:79], v[56:59], v[196:199], v[76:79]
	v_mfma_f32_16x16x32_bf16 v[68:71], v[72:75], v[196:199], v[68:71]
	v_mfma_f32_16x16x32_bf16 v[60:63], v[56:59], v[204:207], v[60:63]
	v_mfma_f32_16x16x32_bf16 v[52:55], v[72:75], v[204:207], v[52:55]
	v_mfma_f32_16x16x32_bf16 v[44:47], v[56:59], v[224:227], v[44:47]
	v_mfma_f32_16x16x32_bf16 v[36:39], v[72:75], v[224:227], v[36:39]
	s_waitcnt lgkmcnt(0)
	v_mfma_f32_16x16x32_bf16 v[12:15], v[56:59], v[246:249], v[12:15]
	v_mfma_f32_16x16x32_bf16 v[4:7], v[72:75], v[246:249], v[4:7]
	s_setprio 1
	s_setprio 0
	v_mfma_f32_16x16x32_bf16 v[16:19], v[152:155], v[192:195], v[16:19]
	v_mfma_f32_16x16x32_bf16 v[72:75], v[160:163], v[196:199], v[16:19]
	v_mfma_f32_16x16x32_bf16 v[16:19], v[168:171], v[192:195], v[20:23]
	v_mfma_f32_16x16x32_bf16 v[64:67], v[176:179], v[196:199], v[16:19]
	v_mfma_f32_16x16x32_bf16 v[16:19], v[152:155], v[200:203], v[24:27]
	v_mfma_f32_16x16x32_bf16 v[56:59], v[160:163], v[204:207], v[16:19]
	v_mfma_f32_16x16x32_bf16 v[16:19], v[168:171], v[200:203], v[28:31]
	v_mfma_f32_16x16x32_bf16 v[48:51], v[176:179], v[204:207], v[16:19]
	v_mfma_f32_16x16x32_bf16 v[16:19], v[152:155], v[220:223], v[40:43]
	v_mfma_f32_16x16x32_bf16 v[40:43], v[160:163], v[224:227], v[16:19]
	v_mfma_f32_16x16x32_bf16 v[16:19], v[168:171], v[220:223], v[32:35]
	v_mfma_f32_16x16x32_bf16 v[8:11], v[152:155], v[228:231], v[8:11]
	v_mfma_f32_16x16x32_bf16 v[0:3], v[168:171], v[228:231], v[0:3]
	v_mfma_f32_16x16x32_bf16 v[32:35], v[176:179], v[224:227], v[16:19]
	v_mfma_f32_16x16x32_bf16 v[8:11], v[160:163], v[246:249], v[8:11]
	v_mfma_f32_16x16x32_bf16 v[0:3], v[176:179], v[246:249], v[0:3]
	s_setprio 1
	s_barrier
	s_add_i32 s6, s6, 2
	s_add_i32 s4, s4, 0x8000
	s_add_i32 s5, s5, 0x8000
	s_cmp_gt_u32 s6, 29
	s_cbranch_scc0 .LBB0_143

.LBB0_594:
	v_add_u32_e32 v80, 0x10000, v226
	ds_read_b128 v[152:155], v80
	ds_read_b128 v[156:159], v80 offset:1024
	ds_read_b128 v[160:163], v80 offset:2048
	ds_read_b128 v[164:167], v80 offset:3072
	v_add_u32_e32 v80, 0x14000, v226
	ds_read_b128 v[168:171], v80
	ds_read_b128 v[172:175], v80 offset:1024
	ds_read_b128 v[176:179], v80 offset:2048
	ds_read_b128 v[180:183], v80 offset:3072
	s_add_i32 s97, s96, s39
	s_add_i32 s94, s97, 0x8000
	s_add_i32 s95, s93, s39
	s_cmp_eq_u32 s39, 0x78000
	s_cselect_b32 s36, vcc_lo, s94
	s_cselect_b32 s95, vcc_hi, s95
	s_or_b32 s94, s36, 0x4000
	ds_read_b128 v[184:187], v227
	ds_read_b128 v[188:191], v227 offset:1024
	ds_read_b128 v[192:195], v227 offset:2048
	ds_read_b128 v[196:199], v227 offset:3072
	ds_read_b128 v[200:203], v227 offset:4096
	ds_read_b128 v[204:207], v227 offset:5120
	ds_read_b128 v[228:231], v227 offset:6144
	ds_read_b128 v[240:243], v227 offset:7168
	s_add_i32 s97, s97, 0x84000
	s_mov_b32 m0, s85
	s_nop 0
	buffer_load_dwordx4 v224, s[60:63], s97 offen lds
	s_nop 0
	s_mov_b32 m0, s86
	s_nop 0
	buffer_load_dwordx4 v225, s[60:63], s97 offen lds
	s_waitcnt vmcnt(8)
	s_waitcnt lgkmcnt(0)
	s_barrier
	s_setprio 0
	s_waitcnt lgkmcnt(7)
	v_mfma_f32_16x16x32_bf16 v[148:151], v[152:155], v[184:187], v[148:151]
	v_mfma_f32_16x16x32_bf16 v[144:147], v[160:163], v[184:187], v[144:147]
	s_waitcnt lgkmcnt(5)
	v_mfma_f32_16x16x32_bf16 v[132:135], v[152:155], v[192:195], v[132:135]
	v_mfma_f32_16x16x32_bf16 v[128:131], v[160:163], v[192:195], v[128:131]
	s_waitcnt lgkmcnt(3)
	v_mfma_f32_16x16x32_bf16 v[116:119], v[152:155], v[200:203], v[116:119]
	v_mfma_f32_16x16x32_bf16 v[112:115], v[160:163], v[200:203], v[112:115]
	s_waitcnt lgkmcnt(1)
	v_mfma_f32_16x16x32_bf16 v[76:79], v[152:155], v[228:231], v[76:79]
	v_mfma_f32_16x16x32_bf16 v[72:75], v[160:163], v[228:231], v[72:75]
	v_mfma_f32_16x16x32_bf16 v[148:151], v[156:159], v[188:191], v[148:151]
	v_mfma_f32_16x16x32_bf16 v[144:147], v[164:167], v[188:191], v[144:147]
	v_mfma_f32_16x16x32_bf16 v[132:135], v[156:159], v[196:199], v[132:135]
	v_mfma_f32_16x16x32_bf16 v[128:131], v[164:167], v[196:199], v[128:131]
	v_mfma_f32_16x16x32_bf16 v[116:119], v[156:159], v[204:207], v[116:119]
	v_mfma_f32_16x16x32_bf16 v[112:115], v[164:167], v[204:207], v[112:115]
	s_waitcnt lgkmcnt(0)
	v_mfma_f32_16x16x32_bf16 v[76:79], v[156:159], v[240:243], v[76:79]
	v_mfma_f32_16x16x32_bf16 v[72:75], v[164:167], v[240:243], v[72:75]
	s_setprio 1
	s_setprio 0
	v_mfma_f32_16x16x32_bf16 v[140:143], v[168:171], v[184:187], v[140:143]
	v_mfma_f32_16x16x32_bf16 v[136:139], v[176:179], v[184:187], v[136:139]
	v_mfma_f32_16x16x32_bf16 v[124:127], v[168:171], v[192:195], v[124:127]
	v_mfma_f32_16x16x32_bf16 v[120:123], v[176:179], v[192:195], v[120:123]
	v_mfma_f32_16x16x32_bf16 v[108:111], v[168:171], v[200:203], v[108:111]
	v_mfma_f32_16x16x32_bf16 v[104:107], v[176:179], v[200:203], v[104:107]
	v_mfma_f32_16x16x32_bf16 v[68:71], v[168:171], v[228:231], v[68:71]
	v_mfma_f32_16x16x32_bf16 v[64:67], v[176:179], v[228:231], v[64:67]
	v_mfma_f32_16x16x32_bf16 v[140:143], v[172:175], v[188:191], v[140:143]
	v_mfma_f32_16x16x32_bf16 v[136:139], v[180:183], v[188:191], v[136:139]
	v_mfma_f32_16x16x32_bf16 v[124:127], v[172:175], v[196:199], v[124:127]
	v_mfma_f32_16x16x32_bf16 v[120:123], v[180:183], v[196:199], v[120:123]
	v_mfma_f32_16x16x32_bf16 v[108:111], v[172:175], v[204:207], v[108:111]
	v_mfma_f32_16x16x32_bf16 v[104:107], v[180:183], v[204:207], v[104:107]
	v_mfma_f32_16x16x32_bf16 v[68:71], v[172:175], v[240:243], v[68:71]
	v_mfma_f32_16x16x32_bf16 v[64:67], v[180:183], v[240:243], v[64:67]
	s_setprio 1
	s_barrier
	ds_read_b128 v[184:187], v227 offset:16384
	ds_read_b128 v[188:191], v227 offset:17408
	ds_read_b128 v[192:195], v227 offset:18432
	ds_read_b128 v[196:199], v227 offset:19456
	ds_read_b128 v[200:203], v227 offset:20480
	ds_read_b128 v[204:207], v227 offset:21504
	ds_read_b128 v[228:231], v227 offset:22528
	ds_read_b128 v[240:243], v227 offset:23552
	s_mov_b32 m0, s34
	s_nop 0
	buffer_load_dwordx4 v224, s[48:51], s95 offen lds
	s_add_i32 s97, s95, 0x80000
	s_mov_b32 m0, s55
	s_nop 0
	buffer_load_dwordx4 v225, s[48:51], s95 offen lds
	s_nop 0
	s_mov_b32 m0, s72
	s_nop 0
	buffer_load_dwordx4 v224, s[48:51], s97 offen lds
	s_nop 0
	s_mov_b32 m0, s73
	s_nop 0
	buffer_load_dwordx4 v225, s[48:51], s97 offen lds
	s_nop 0
	s_mov_b32 m0, s31
	s_nop 0
	buffer_load_dwordx4 v224, s[60:63], s36 offen lds
	s_nop 0
	s_mov_b32 m0, s74
	s_nop 0
	buffer_load_dwordx4 v225, s[60:63], s36 offen lds
	s_waitcnt vmcnt(8)
	s_waitcnt lgkmcnt(0)
	s_barrier
	s_setprio 0
	s_waitcnt lgkmcnt(7)
	v_mfma_f32_16x16x32_bf16 v[60:63], v[152:155], v[184:187], v[60:63]
	v_mfma_f32_16x16x32_bf16 v[56:59], v[160:163], v[184:187], v[56:59]
	s_waitcnt lgkmcnt(5)
	v_mfma_f32_16x16x32_bf16 v[44:47], v[152:155], v[192:195], v[44:47]
	v_mfma_f32_16x16x32_bf16 v[40:43], v[160:163], v[192:195], v[40:43]
	s_waitcnt lgkmcnt(3)
	v_mfma_f32_16x16x32_bf16 v[28:31], v[152:155], v[200:203], v[28:31]
	v_mfma_f32_16x16x32_bf16 v[24:27], v[160:163], v[200:203], v[24:27]
	s_waitcnt lgkmcnt(1)
	v_mfma_f32_16x16x32_bf16 v[12:15], v[152:155], v[228:231], v[12:15]
	v_mfma_f32_16x16x32_bf16 v[8:11], v[160:163], v[228:231], v[8:11]
	v_mfma_f32_16x16x32_bf16 v[60:63], v[156:159], v[188:191], v[60:63]
	v_mfma_f32_16x16x32_bf16 v[56:59], v[164:167], v[188:191], v[56:59]
	v_mfma_f32_16x16x32_bf16 v[44:47], v[156:159], v[196:199], v[44:47]
	v_mfma_f32_16x16x32_bf16 v[40:43], v[164:167], v[196:199], v[40:43]
	v_mfma_f32_16x16x32_bf16 v[28:31], v[156:159], v[204:207], v[28:31]
	v_mfma_f32_16x16x32_bf16 v[24:27], v[164:167], v[204:207], v[24:27]
	s_waitcnt lgkmcnt(0)
	v_mfma_f32_16x16x32_bf16 v[12:15], v[156:159], v[240:243], v[12:15]
	v_mfma_f32_16x16x32_bf16 v[8:11], v[164:167], v[240:243], v[8:11]
	s_setprio 1
	s_setprio 0
	v_mfma_f32_16x16x32_bf16 v[52:55], v[168:171], v[184:187], v[52:55]
	v_mfma_f32_16x16x32_bf16 v[48:51], v[176:179], v[184:187], v[48:51]
	v_mfma_f32_16x16x32_bf16 v[36:39], v[168:171], v[192:195], v[36:39]
	v_mfma_f32_16x16x32_bf16 v[32:35], v[176:179], v[192:195], v[32:35]
	v_mfma_f32_16x16x32_bf16 v[20:23], v[168:171], v[200:203], v[20:23]
	v_mfma_f32_16x16x32_bf16 v[16:19], v[176:179], v[200:203], v[16:19]
	v_mfma_f32_16x16x32_bf16 v[4:7], v[168:171], v[228:231], v[4:7]
	v_mfma_f32_16x16x32_bf16 v[0:3], v[176:179], v[228:231], v[0:3]
	v_mfma_f32_16x16x32_bf16 v[52:55], v[172:175], v[188:191], v[52:55]
	v_mfma_f32_16x16x32_bf16 v[48:51], v[180:183], v[188:191], v[48:51]
	v_mfma_f32_16x16x32_bf16 v[36:39], v[172:175], v[196:199], v[36:39]
	v_mfma_f32_16x16x32_bf16 v[32:35], v[180:183], v[196:199], v[32:35]
	v_mfma_f32_16x16x32_bf16 v[20:23], v[172:175], v[204:207], v[20:23]
	v_mfma_f32_16x16x32_bf16 v[16:19], v[180:183], v[204:207], v[16:19]
	v_mfma_f32_16x16x32_bf16 v[4:7], v[172:175], v[240:243], v[4:7]
	v_mfma_f32_16x16x32_bf16 v[0:3], v[180:183], v[240:243], v[0:3]
	s_setprio 1
	s_barrier
	v_add_u32_e32 v80, 0x18000, v226
	ds_read_b128 v[152:155], v80
	ds_read_b128 v[156:159], v80 offset:1024
	ds_read_b128 v[160:163], v80 offset:2048
	ds_read_b128 v[164:167], v80 offset:3072
	v_add_u32_e32 v80, 0x1c000, v226
	ds_read_b128 v[168:171], v80
	ds_read_b128 v[172:175], v80 offset:1024
	ds_read_b128 v[176:179], v80 offset:2048
	ds_read_b128 v[180:183], v80 offset:3072
	ds_read_b128 v[184:187], v227 offset:32768
	ds_read_b128 v[188:191], v227 offset:33792
	ds_read_b128 v[192:195], v227 offset:34816
	ds_read_b128 v[196:199], v227 offset:35840
	ds_read_b128 v[200:203], v227 offset:36864
	ds_read_b128 v[204:207], v227 offset:37888
	ds_read_b128 v[228:231], v227 offset:38912
	ds_read_b128 v[240:243], v227 offset:39936
	s_add_i32 s36, s36, 0x80000
	s_mov_b32 m0, s75
	s_nop 0
	buffer_load_dwordx4 v224, s[60:63], s36 offen lds
	s_nop 0
	s_mov_b32 m0, s76
	s_nop 0
	buffer_load_dwordx4 v225, s[60:63], s36 offen lds
	s_waitcnt vmcnt(8)
	s_waitcnt lgkmcnt(0)
	s_barrier
	s_setprio 0
	s_waitcnt lgkmcnt(7)
	v_mfma_f32_16x16x32_bf16 v[148:151], v[152:155], v[184:187], v[148:151]
	v_mfma_f32_16x16x32_bf16 v[144:147], v[160:163], v[184:187], v[144:147]
	s_waitcnt lgkmcnt(5)
	v_mfma_f32_16x16x32_bf16 v[132:135], v[152:155], v[192:195], v[132:135]
	v_mfma_f32_16x16x32_bf16 v[128:131], v[160:163], v[192:195], v[128:131]
	s_waitcnt lgkmcnt(3)
	v_mfma_f32_16x16x32_bf16 v[116:119], v[152:155], v[200:203], v[116:119]
	v_mfma_f32_16x16x32_bf16 v[112:115], v[160:163], v[200:203], v[112:115]
	s_waitcnt lgkmcnt(1)
	v_mfma_f32_16x16x32_bf16 v[76:79], v[152:155], v[228:231], v[76:79]
	v_mfma_f32_16x16x32_bf16 v[72:75], v[160:163], v[228:231], v[72:75]
	v_mfma_f32_16x16x32_bf16 v[148:151], v[156:159], v[188:191], v[148:151]
	v_mfma_f32_16x16x32_bf16 v[144:147], v[164:167], v[188:191], v[144:147]
	v_mfma_f32_16x16x32_bf16 v[132:135], v[156:159], v[196:199], v[132:135]
	v_mfma_f32_16x16x32_bf16 v[128:131], v[164:167], v[196:199], v[128:131]
	v_mfma_f32_16x16x32_bf16 v[116:119], v[156:159], v[204:207], v[116:119]
	v_mfma_f32_16x16x32_bf16 v[112:115], v[164:167], v[204:207], v[112:115]
	s_waitcnt lgkmcnt(0)
	v_mfma_f32_16x16x32_bf16 v[76:79], v[156:159], v[240:243], v[76:79]
	v_mfma_f32_16x16x32_bf16 v[72:75], v[164:167], v[240:243], v[72:75]
	s_setprio 1
	s_setprio 0
	v_mfma_f32_16x16x32_bf16 v[140:143], v[168:171], v[184:187], v[140:143]
	v_mfma_f32_16x16x32_bf16 v[136:139], v[176:179], v[184:187], v[136:139]
	v_mfma_f32_16x16x32_bf16 v[124:127], v[168:171], v[192:195], v[124:127]
	v_mfma_f32_16x16x32_bf16 v[120:123], v[176:179], v[192:195], v[120:123]
	v_mfma_f32_16x16x32_bf16 v[108:111], v[168:171], v[200:203], v[108:111]
	v_mfma_f32_16x16x32_bf16 v[104:107], v[176:179], v[200:203], v[104:107]
	v_mfma_f32_16x16x32_bf16 v[68:71], v[168:171], v[228:231], v[68:71]
	v_mfma_f32_16x16x32_bf16 v[64:67], v[176:179], v[228:231], v[64:67]
	v_mfma_f32_16x16x32_bf16 v[140:143], v[172:175], v[188:191], v[140:143]
	v_mfma_f32_16x16x32_bf16 v[136:139], v[180:183], v[188:191], v[136:139]
	v_mfma_f32_16x16x32_bf16 v[124:127], v[172:175], v[196:199], v[124:127]
	v_mfma_f32_16x16x32_bf16 v[120:123], v[180:183], v[196:199], v[120:123]
	v_mfma_f32_16x16x32_bf16 v[108:111], v[172:175], v[204:207], v[108:111]
	v_mfma_f32_16x16x32_bf16 v[104:107], v[180:183], v[204:207], v[104:107]
	v_mfma_f32_16x16x32_bf16 v[68:71], v[172:175], v[240:243], v[68:71]
	v_mfma_f32_16x16x32_bf16 v[64:67], v[180:183], v[240:243], v[64:67]
	s_setprio 1
	s_barrier
	ds_read_b128 v[184:187], v227 offset:49152
	ds_read_b128 v[188:191], v227 offset:50176
	ds_read_b128 v[192:195], v227 offset:51200
	ds_read_b128 v[196:199], v227 offset:52224
	ds_read_b128 v[200:203], v227 offset:53248
	ds_read_b128 v[204:207], v227 offset:54272
	ds_read_b128 v[228:231], v227 offset:55296
	ds_read_b128 v[240:243], v227 offset:56320
	s_or_b32 s36, s95, 0x4000
	s_mov_b32 m0, s77
	s_nop 0
	buffer_load_dwordx4 v224, s[48:51], s36 offen lds
	s_nop 0
	s_mov_b32 m0, s78
	s_nop 0
	buffer_load_dwordx4 v225, s[48:51], s36 offen lds
	s_add_i32 s36, s95, 0x84000
	s_mov_b32 m0, s83
	s_nop 0
	buffer_load_dwordx4 v224, s[48:51], s36 offen lds
	s_nop 0
	s_mov_b32 m0, s84
	s_nop 0
	buffer_load_dwordx4 v225, s[48:51], s36 offen lds
	s_nop 0
	s_mov_b32 m0, s79
	s_nop 0
	buffer_load_dwordx4 v224, s[60:63], s94 offen lds
	s_nop 0
	s_mov_b32 m0, s82
	s_nop 0
	buffer_load_dwordx4 v225, s[60:63], s94 offen lds
	s_waitcnt vmcnt(8)
	s_waitcnt lgkmcnt(0)
	s_barrier
	s_setprio 0
	s_waitcnt lgkmcnt(7)
	v_mfma_f32_16x16x32_bf16 v[60:63], v[152:155], v[184:187], v[60:63]
	v_mfma_f32_16x16x32_bf16 v[56:59], v[160:163], v[184:187], v[56:59]
	s_waitcnt lgkmcnt(5)
	v_mfma_f32_16x16x32_bf16 v[44:47], v[152:155], v[192:195], v[44:47]
	v_mfma_f32_16x16x32_bf16 v[40:43], v[160:163], v[192:195], v[40:43]
	s_waitcnt lgkmcnt(3)
	v_mfma_f32_16x16x32_bf16 v[28:31], v[152:155], v[200:203], v[28:31]
	v_mfma_f32_16x16x32_bf16 v[24:27], v[160:163], v[200:203], v[24:27]
	s_waitcnt lgkmcnt(1)
	v_mfma_f32_16x16x32_bf16 v[12:15], v[152:155], v[228:231], v[12:15]
	v_mfma_f32_16x16x32_bf16 v[8:11], v[160:163], v[228:231], v[8:11]
	v_mfma_f32_16x16x32_bf16 v[60:63], v[156:159], v[188:191], v[60:63]
	v_mfma_f32_16x16x32_bf16 v[56:59], v[164:167], v[188:191], v[56:59]
	v_mfma_f32_16x16x32_bf16 v[44:47], v[156:159], v[196:199], v[44:47]
	v_mfma_f32_16x16x32_bf16 v[40:43], v[164:167], v[196:199], v[40:43]
	v_mfma_f32_16x16x32_bf16 v[28:31], v[156:159], v[204:207], v[28:31]
	v_mfma_f32_16x16x32_bf16 v[24:27], v[164:167], v[204:207], v[24:27]
	s_waitcnt lgkmcnt(0)
	v_mfma_f32_16x16x32_bf16 v[12:15], v[156:159], v[240:243], v[12:15]
	v_mfma_f32_16x16x32_bf16 v[8:11], v[164:167], v[240:243], v[8:11]
	s_setprio 1
	s_setprio 0
	v_mfma_f32_16x16x32_bf16 v[52:55], v[168:171], v[184:187], v[52:55]
	v_mfma_f32_16x16x32_bf16 v[48:51], v[176:179], v[184:187], v[48:51]
	v_mfma_f32_16x16x32_bf16 v[36:39], v[168:171], v[192:195], v[36:39]
	v_mfma_f32_16x16x32_bf16 v[32:35], v[176:179], v[192:195], v[32:35]
	v_mfma_f32_16x16x32_bf16 v[20:23], v[168:171], v[200:203], v[20:23]
	v_mfma_f32_16x16x32_bf16 v[16:19], v[176:179], v[200:203], v[16:19]
	v_mfma_f32_16x16x32_bf16 v[4:7], v[168:171], v[228:231], v[4:7]
	v_mfma_f32_16x16x32_bf16 v[0:3], v[176:179], v[228:231], v[0:3]
	v_mfma_f32_16x16x32_bf16 v[52:55], v[172:175], v[188:191], v[52:55]
	v_mfma_f32_16x16x32_bf16 v[48:51], v[180:183], v[188:191], v[48:51]
	v_mfma_f32_16x16x32_bf16 v[36:39], v[172:175], v[196:199], v[36:39]
	v_mfma_f32_16x16x32_bf16 v[32:35], v[180:183], v[196:199], v[32:35]
	v_mfma_f32_16x16x32_bf16 v[20:23], v[172:175], v[204:207], v[20:23]
	v_mfma_f32_16x16x32_bf16 v[16:19], v[180:183], v[204:207], v[16:19]
	v_mfma_f32_16x16x32_bf16 v[4:7], v[172:175], v[240:243], v[4:7]
	v_mfma_f32_16x16x32_bf16 v[0:3], v[180:183], v[240:243], v[0:3]
	s_setprio 1
	s_barrier
	s_add_i32 s38, s38, 2
	s_add_i32 s39, s39, 0x8000
	s_cmp_gt_u32 s38, 29
	s_cbranch_scc1 .LBB0_597

.Lnb_p4:
	s_add_i32 s11, s8, 0xfff84000
	s_cmp_eq_u32 s10, 28
	s_cselect_b32 s13, s6, s11
	s_cselect_b32 s12, s7, s9
	s_or_b32 s11, s13, 0x4000
	s_mov_b32 m0, s89
	s_nop 0
	buffer_load_dwordx4 v220, s[64:67], s8 offen lds
	s_nop 0
	s_mov_b32 m0, s91
	s_nop 0
	buffer_load_dwordx4 v221, s[64:67], s8 offen lds
	s_waitcnt vmcnt(24)
	s_waitcnt lgkmcnt(0)
	s_barrier
	s_setprio 0
	s_waitcnt lgkmcnt(7)
	v_mfma_f32_16x16x32_bf16 v[164:167], v[128:131], v[184:187], 0
	v_mfma_f32_16x16x32_bf16 v[160:163], v[152:155], v[184:187], 0
	s_waitcnt lgkmcnt(5)
	v_mfma_f32_16x16x32_bf16 v[136:139], v[128:131], v[192:195], 0
	v_mfma_f32_16x16x32_bf16 v[132:135], v[152:155], v[192:195], 0
	s_waitcnt lgkmcnt(3)
	v_mfma_f32_16x16x32_bf16 v[116:119], v[128:131], v[200:203], 0
	v_mfma_f32_16x16x32_bf16 v[112:115], v[152:155], v[200:203], 0
	s_waitcnt lgkmcnt(1)
	v_mfma_f32_16x16x32_bf16 v[76:79], v[128:131], v[224:227], 0
	v_mfma_f32_16x16x32_bf16 v[72:75], v[152:155], v[224:227], 0
	v_mfma_f32_16x16x32_bf16 v[164:167], v[140:143], v[188:191], v[164:167]
	v_mfma_f32_16x16x32_bf16 v[160:163], v[156:159], v[188:191], v[160:163]
	v_mfma_f32_16x16x32_bf16 v[136:139], v[140:143], v[196:199], v[136:139]
	v_mfma_f32_16x16x32_bf16 v[132:135], v[156:159], v[196:199], v[132:135]
	v_mfma_f32_16x16x32_bf16 v[116:119], v[140:143], v[204:207], v[116:119]
	v_mfma_f32_16x16x32_bf16 v[112:115], v[156:159], v[204:207], v[112:115]
	s_waitcnt lgkmcnt(0)
	v_mfma_f32_16x16x32_bf16 v[76:79], v[140:143], v[228:231], v[76:79]
	v_mfma_f32_16x16x32_bf16 v[72:75], v[156:159], v[228:231], v[72:75]
	s_setprio 1
	s_setprio 0
	v_mfma_f32_16x16x32_bf16 v[148:151], v[168:171], v[184:187], 0
	v_mfma_f32_16x16x32_bf16 v[144:147], v[176:179], v[184:187], 0
	v_mfma_f32_16x16x32_bf16 v[124:127], v[168:171], v[192:195], 0
	v_mfma_f32_16x16x32_bf16 v[120:123], v[176:179], v[192:195], 0
	v_mfma_f32_16x16x32_bf16 v[108:111], v[168:171], v[200:203], 0
	v_mfma_f32_16x16x32_bf16 v[104:107], v[176:179], v[200:203], 0
	v_mfma_f32_16x16x32_bf16 v[68:71], v[168:171], v[224:227], 0
	v_mfma_f32_16x16x32_bf16 v[64:67], v[176:179], v[224:227], 0
	v_mfma_f32_16x16x32_bf16 v[148:151], v[172:175], v[188:191], v[148:151]
	v_mfma_f32_16x16x32_bf16 v[144:147], v[180:183], v[188:191], v[144:147]
	v_mfma_f32_16x16x32_bf16 v[124:127], v[172:175], v[196:199], v[124:127]
	v_mfma_f32_16x16x32_bf16 v[120:123], v[180:183], v[196:199], v[120:123]
	v_mfma_f32_16x16x32_bf16 v[108:111], v[172:175], v[204:207], v[108:111]
	v_mfma_f32_16x16x32_bf16 v[104:107], v[180:183], v[204:207], v[104:107]
	v_mfma_f32_16x16x32_bf16 v[68:71], v[172:175], v[228:231], v[68:71]
	v_mfma_f32_16x16x32_bf16 v[64:67], v[180:183], v[228:231], v[64:67]
	s_setprio 1
	s_barrier
	ds_read_b128 v[184:187], v223 offset:16384
	ds_read_b128 v[188:191], v223 offset:17408
	ds_read_b128 v[192:195], v223 offset:18432
	ds_read_b128 v[196:199], v223 offset:19456
	ds_read_b128 v[200:203], v223 offset:20480
	ds_read_b128 v[204:207], v223 offset:21504
	ds_read_b128 v[224:227], v223 offset:22528
	ds_read_b128 v[228:231], v223 offset:23552
	s_mov_b32 m0, s55
	s_nop 0
	buffer_load_dwordx4 v220, s[48:51], s12 offen lds
	s_add_i32 s14, s12, 0x80000
	s_mov_b32 m0, s76
	s_nop 0
	buffer_load_dwordx4 v221, s[48:51], s12 offen lds
	s_nop 0
	s_mov_b32 m0, s77
	s_nop 0
	buffer_load_dwordx4 v220, s[48:51], s14 offen lds
	s_nop 0
	s_mov_b32 m0, s78
	s_nop 0
	buffer_load_dwordx4 v221, s[48:51], s14 offen lds
	s_nop 0
	s_mov_b32 m0, s31
	s_nop 0
	buffer_load_dwordx4 v220, s[64:67], s13 offen lds
	s_nop 0
	s_mov_b32 m0, s79
	s_nop 0
	buffer_load_dwordx4 v221, s[64:67], s13 offen lds
	s_waitcnt vmcnt(24)
	s_waitcnt lgkmcnt(0)
	s_barrier
	s_setprio 0
	s_waitcnt lgkmcnt(7)
	v_mfma_f32_16x16x32_bf16 v[60:63], v[128:131], v[184:187], 0
	v_mfma_f32_16x16x32_bf16 v[56:59], v[152:155], v[184:187], 0
	s_waitcnt lgkmcnt(5)
	v_mfma_f32_16x16x32_bf16 v[44:47], v[128:131], v[192:195], 0
	v_mfma_f32_16x16x32_bf16 v[40:43], v[152:155], v[192:195], 0
	s_waitcnt lgkmcnt(3)
	v_mfma_f32_16x16x32_bf16 v[28:31], v[128:131], v[200:203], 0
	v_mfma_f32_16x16x32_bf16 v[24:27], v[152:155], v[200:203], 0
	s_waitcnt lgkmcnt(1)
	v_mfma_f32_16x16x32_bf16 v[12:15], v[128:131], v[224:227], 0
	v_mfma_f32_16x16x32_bf16 v[8:11], v[152:155], v[224:227], 0
	v_mfma_f32_16x16x32_bf16 v[60:63], v[140:143], v[188:191], v[60:63]
	v_mfma_f32_16x16x32_bf16 v[56:59], v[156:159], v[188:191], v[56:59]
	v_mfma_f32_16x16x32_bf16 v[44:47], v[140:143], v[196:199], v[44:47]
	v_mfma_f32_16x16x32_bf16 v[40:43], v[156:159], v[196:199], v[40:43]
	v_mfma_f32_16x16x32_bf16 v[28:31], v[140:143], v[204:207], v[28:31]
	v_mfma_f32_16x16x32_bf16 v[24:27], v[156:159], v[204:207], v[24:27]
	s_waitcnt lgkmcnt(0)
	v_mfma_f32_16x16x32_bf16 v[12:15], v[140:143], v[228:231], v[12:15]
	v_mfma_f32_16x16x32_bf16 v[8:11], v[156:159], v[228:231], v[8:11]
	s_setprio 1
	s_setprio 0
	v_mfma_f32_16x16x32_bf16 v[52:55], v[168:171], v[184:187], 0
	v_mfma_f32_16x16x32_bf16 v[48:51], v[176:179], v[184:187], 0
	v_mfma_f32_16x16x32_bf16 v[36:39], v[168:171], v[192:195], 0
	v_mfma_f32_16x16x32_bf16 v[32:35], v[176:179], v[192:195], 0
	v_mfma_f32_16x16x32_bf16 v[20:23], v[168:171], v[200:203], 0
	v_mfma_f32_16x16x32_bf16 v[16:19], v[176:179], v[200:203], 0
	v_mfma_f32_16x16x32_bf16 v[4:7], v[168:171], v[224:227], 0
	v_mfma_f32_16x16x32_bf16 v[0:3], v[176:179], v[224:227], 0
	v_mfma_f32_16x16x32_bf16 v[52:55], v[172:175], v[188:191], v[52:55]
	v_mfma_f32_16x16x32_bf16 v[48:51], v[180:183], v[188:191], v[48:51]
	v_mfma_f32_16x16x32_bf16 v[36:39], v[172:175], v[196:199], v[36:39]
	v_mfma_f32_16x16x32_bf16 v[32:35], v[180:183], v[196:199], v[32:35]
	v_mfma_f32_16x16x32_bf16 v[20:23], v[172:175], v[204:207], v[20:23]
	v_mfma_f32_16x16x32_bf16 v[16:19], v[180:183], v[204:207], v[16:19]
	v_mfma_f32_16x16x32_bf16 v[4:7], v[172:175], v[228:231], v[4:7]
	v_mfma_f32_16x16x32_bf16 v[0:3], v[180:183], v[228:231], v[0:3]
	s_setprio 1
	s_barrier
	v_add_u32_e32 v156, 0x18000, v222
	v_add_u32_e32 v180, 0x1c000, v222
	ds_read_b128 v[128:131], v156
	ds_read_b128 v[140:143], v156 offset:1024
	ds_read_b128 v[152:155], v156 offset:2048
	ds_read_b128 v[156:159], v156 offset:3072
	ds_read_b128 v[168:171], v180
	ds_read_b128 v[172:175], v180 offset:1024
	ds_read_b128 v[176:179], v180 offset:2048
	ds_read_b128 v[180:183], v180 offset:3072
	ds_read_b128 v[184:187], v223 offset:32768
	ds_read_b128 v[188:191], v223 offset:33792
	ds_read_b128 v[192:195], v223 offset:34816
	ds_read_b128 v[196:199], v223 offset:35840
	ds_read_b128 v[200:203], v223 offset:36864
	ds_read_b128 v[204:207], v223 offset:37888
	ds_read_b128 v[224:227], v223 offset:38912
	ds_read_b128 v[228:231], v223 offset:39936
	s_add_i32 s13, s13, 0x80000
	s_mov_b32 m0, s82
	s_nop 0
	buffer_load_dwordx4 v220, s[64:67], s13 offen lds
	s_nop 0
	s_mov_b32 m0, s83
	s_nop 0
	buffer_load_dwordx4 v221, s[64:67], s13 offen lds
	s_waitcnt vmcnt(8)
	s_waitcnt lgkmcnt(0)
	s_barrier
	s_setprio 0
	s_waitcnt lgkmcnt(7)
	v_mfma_f32_16x16x32_bf16 v[164:167], v[128:131], v[184:187], v[164:167]
	v_mfma_f32_16x16x32_bf16 v[160:163], v[152:155], v[184:187], v[160:163]
	s_waitcnt lgkmcnt(5)
	v_mfma_f32_16x16x32_bf16 v[136:139], v[128:131], v[192:195], v[136:139]
	v_mfma_f32_16x16x32_bf16 v[132:135], v[152:155], v[192:195], v[132:135]
	s_waitcnt lgkmcnt(3)
	v_mfma_f32_16x16x32_bf16 v[116:119], v[128:131], v[200:203], v[116:119]
	v_mfma_f32_16x16x32_bf16 v[112:115], v[152:155], v[200:203], v[112:115]
	s_waitcnt lgkmcnt(1)
	v_mfma_f32_16x16x32_bf16 v[76:79], v[128:131], v[224:227], v[76:79]
	v_mfma_f32_16x16x32_bf16 v[72:75], v[152:155], v[224:227], v[72:75]
	v_mfma_f32_16x16x32_bf16 v[164:167], v[140:143], v[188:191], v[164:167]
	v_mfma_f32_16x16x32_bf16 v[160:163], v[156:159], v[188:191], v[160:163]
	v_mfma_f32_16x16x32_bf16 v[136:139], v[140:143], v[196:199], v[136:139]
	v_mfma_f32_16x16x32_bf16 v[132:135], v[156:159], v[196:199], v[132:135]
	v_mfma_f32_16x16x32_bf16 v[116:119], v[140:143], v[204:207], v[116:119]
	v_mfma_f32_16x16x32_bf16 v[112:115], v[156:159], v[204:207], v[112:115]
	s_waitcnt lgkmcnt(0)
	v_mfma_f32_16x16x32_bf16 v[76:79], v[140:143], v[228:231], v[76:79]
	v_mfma_f32_16x16x32_bf16 v[72:75], v[156:159], v[228:231], v[72:75]
	s_setprio 1
	s_setprio 0
	v_mfma_f32_16x16x32_bf16 v[148:151], v[168:171], v[184:187], v[148:151]
	v_mfma_f32_16x16x32_bf16 v[144:147], v[176:179], v[184:187], v[144:147]
	v_mfma_f32_16x16x32_bf16 v[124:127], v[168:171], v[192:195], v[124:127]
	v_mfma_f32_16x16x32_bf16 v[120:123], v[176:179], v[192:195], v[120:123]
	v_mfma_f32_16x16x32_bf16 v[108:111], v[168:171], v[200:203], v[108:111]
	v_mfma_f32_16x16x32_bf16 v[104:107], v[176:179], v[200:203], v[104:107]
	v_mfma_f32_16x16x32_bf16 v[68:71], v[168:171], v[224:227], v[68:71]
	v_mfma_f32_16x16x32_bf16 v[64:67], v[176:179], v[224:227], v[64:67]
	v_mfma_f32_16x16x32_bf16 v[148:151], v[172:175], v[188:191], v[148:151]
	v_mfma_f32_16x16x32_bf16 v[144:147], v[180:183], v[188:191], v[144:147]
	v_mfma_f32_16x16x32_bf16 v[124:127], v[172:175], v[196:199], v[124:127]
	v_mfma_f32_16x16x32_bf16 v[120:123], v[180:183], v[196:199], v[120:123]
	v_mfma_f32_16x16x32_bf16 v[108:111], v[172:175], v[204:207], v[108:111]
	v_mfma_f32_16x16x32_bf16 v[104:107], v[180:183], v[204:207], v[104:107]
	v_mfma_f32_16x16x32_bf16 v[68:71], v[172:175], v[228:231], v[68:71]
	v_mfma_f32_16x16x32_bf16 v[64:67], v[180:183], v[228:231], v[64:67]
	s_setprio 1
	s_barrier
	ds_read_b128 v[184:187], v223 offset:49152
	ds_read_b128 v[188:191], v223 offset:50176
	ds_read_b128 v[192:195], v223 offset:51200
	ds_read_b128 v[196:199], v223 offset:52224
	ds_read_b128 v[200:203], v223 offset:53248
	ds_read_b128 v[204:207], v223 offset:54272
	ds_read_b128 v[224:227], v223 offset:55296
	ds_read_b128 v[228:231], v223 offset:56320
	s_or_b32 s13, s12, 0x4000
	s_mov_b32 m0, s34
	s_nop 0
	buffer_load_dwordx4 v220, s[48:51], s13 offen lds
	s_add_i32 s12, s12, 0x84000
	s_mov_b32 m0, s84
	s_nop 0
	buffer_load_dwordx4 v221, s[48:51], s13 offen lds
	s_nop 0
	s_mov_b32 m0, s87
	s_nop 0
	buffer_load_dwordx4 v220, s[48:51], s12 offen lds
	s_nop 0
	s_mov_b32 m0, s88
	s_nop 0
	buffer_load_dwordx4 v221, s[48:51], s12 offen lds
	s_nop 0
	s_mov_b32 m0, s85
	s_nop 0
	buffer_load_dwordx4 v220, s[64:67], s11 offen lds
	s_nop 0
	s_mov_b32 m0, s86
	s_nop 0
	buffer_load_dwordx4 v221, s[64:67], s11 offen lds
	s_waitcnt vmcnt(8)
	s_waitcnt lgkmcnt(0)
	s_barrier
	s_setprio 0
	s_waitcnt lgkmcnt(7)
	v_mfma_f32_16x16x32_bf16 v[60:63], v[128:131], v[184:187], v[60:63]
	v_mfma_f32_16x16x32_bf16 v[56:59], v[152:155], v[184:187], v[56:59]
	s_waitcnt lgkmcnt(5)
	v_mfma_f32_16x16x32_bf16 v[44:47], v[128:131], v[192:195], v[44:47]
	v_mfma_f32_16x16x32_bf16 v[40:43], v[152:155], v[192:195], v[40:43]
	s_waitcnt lgkmcnt(3)
	v_mfma_f32_16x16x32_bf16 v[28:31], v[128:131], v[200:203], v[28:31]
	v_mfma_f32_16x16x32_bf16 v[24:27], v[152:155], v[200:203], v[24:27]
	s_waitcnt lgkmcnt(1)
	v_mfma_f32_16x16x32_bf16 v[12:15], v[128:131], v[224:227], v[12:15]
	v_mfma_f32_16x16x32_bf16 v[8:11], v[152:155], v[224:227], v[8:11]
	v_mfma_f32_16x16x32_bf16 v[60:63], v[140:143], v[188:191], v[60:63]
	v_mfma_f32_16x16x32_bf16 v[56:59], v[156:159], v[188:191], v[56:59]
	v_mfma_f32_16x16x32_bf16 v[44:47], v[140:143], v[196:199], v[44:47]
	v_mfma_f32_16x16x32_bf16 v[40:43], v[156:159], v[196:199], v[40:43]
	v_mfma_f32_16x16x32_bf16 v[28:31], v[140:143], v[204:207], v[28:31]
	v_mfma_f32_16x16x32_bf16 v[24:27], v[156:159], v[204:207], v[24:27]
	s_waitcnt lgkmcnt(0)
	v_mfma_f32_16x16x32_bf16 v[12:15], v[140:143], v[228:231], v[12:15]
	v_mfma_f32_16x16x32_bf16 v[8:11], v[156:159], v[228:231], v[8:11]
	s_setprio 1
	s_setprio 0
	v_mfma_f32_16x16x32_bf16 v[52:55], v[168:171], v[184:187], v[52:55]
	v_mfma_f32_16x16x32_bf16 v[48:51], v[176:179], v[184:187], v[48:51]
	v_mfma_f32_16x16x32_bf16 v[36:39], v[168:171], v[192:195], v[36:39]
	v_mfma_f32_16x16x32_bf16 v[32:35], v[176:179], v[192:195], v[32:35]
	v_mfma_f32_16x16x32_bf16 v[20:23], v[168:171], v[200:203], v[20:23]
	v_mfma_f32_16x16x32_bf16 v[16:19], v[176:179], v[200:203], v[16:19]
	v_mfma_f32_16x16x32_bf16 v[4:7], v[168:171], v[224:227], v[4:7]
	v_mfma_f32_16x16x32_bf16 v[0:3], v[176:179], v[224:227], v[0:3]
	v_mfma_f32_16x16x32_bf16 v[52:55], v[172:175], v[188:191], v[52:55]
	v_mfma_f32_16x16x32_bf16 v[48:51], v[180:183], v[188:191], v[48:51]
	v_mfma_f32_16x16x32_bf16 v[36:39], v[172:175], v[196:199], v[36:39]
	v_mfma_f32_16x16x32_bf16 v[32:35], v[180:183], v[196:199], v[32:35]
	v_mfma_f32_16x16x32_bf16 v[20:23], v[172:175], v[204:207], v[20:23]
	v_mfma_f32_16x16x32_bf16 v[16:19], v[180:183], v[204:207], v[16:19]
	v_mfma_f32_16x16x32_bf16 v[4:7], v[172:175], v[228:231], v[4:7]
	v_mfma_f32_16x16x32_bf16 v[0:3], v[180:183], v[228:231], v[0:3]
	s_setprio 1
	s_barrier
	s_add_i32 s10, s10, 2
	s_add_i32 s8, s8, 0x8000
	s_add_i32 s9, s9, 0x8000
.LBB0_691:
	v_add_u32_e32 v156, 0x10000, v222
	v_add_u32_e32 v180, 0x14000, v222
	ds_read_b128 v[128:131], v156
	ds_read_b128 v[140:143], v156 offset:1024
	ds_read_b128 v[152:155], v156 offset:2048
	ds_read_b128 v[156:159], v156 offset:3072
	ds_read_b128 v[168:171], v180
	ds_read_b128 v[172:175], v180 offset:1024
	ds_read_b128 v[176:179], v180 offset:2048
	ds_read_b128 v[180:183], v180 offset:3072
	s_add_i32 s11, s8, 0xfff84000
	s_cmp_eq_u32 s10, 28
	s_cselect_b32 s13, s6, s11
	s_cselect_b32 s12, s7, s9
	s_or_b32 s11, s13, 0x4000
	ds_read_b128 v[184:187], v223
	ds_read_b128 v[188:191], v223 offset:1024
	ds_read_b128 v[192:195], v223 offset:2048
	ds_read_b128 v[196:199], v223 offset:3072
	ds_read_b128 v[200:203], v223 offset:4096
	ds_read_b128 v[204:207], v223 offset:5120
	ds_read_b128 v[224:227], v223 offset:6144
	ds_read_b128 v[228:231], v223 offset:7168
	s_mov_b32 m0, s89
	s_nop 0
	buffer_load_dwordx4 v220, s[64:67], s8 offen lds
	s_nop 0
	s_mov_b32 m0, s91
	s_nop 0
	buffer_load_dwordx4 v221, s[64:67], s8 offen lds
	s_waitcnt vmcnt(8)
	s_waitcnt lgkmcnt(0)
	s_barrier
	s_setprio 0
	s_waitcnt lgkmcnt(7)
	v_mfma_f32_16x16x32_bf16 v[164:167], v[128:131], v[184:187], v[164:167]
	v_mfma_f32_16x16x32_bf16 v[160:163], v[152:155], v[184:187], v[160:163]
	s_waitcnt lgkmcnt(5)
	v_mfma_f32_16x16x32_bf16 v[136:139], v[128:131], v[192:195], v[136:139]
	v_mfma_f32_16x16x32_bf16 v[132:135], v[152:155], v[192:195], v[132:135]
	s_waitcnt lgkmcnt(3)
	v_mfma_f32_16x16x32_bf16 v[116:119], v[128:131], v[200:203], v[116:119]
	v_mfma_f32_16x16x32_bf16 v[112:115], v[152:155], v[200:203], v[112:115]
	s_waitcnt lgkmcnt(1)
	v_mfma_f32_16x16x32_bf16 v[76:79], v[128:131], v[224:227], v[76:79]
	v_mfma_f32_16x16x32_bf16 v[72:75], v[152:155], v[224:227], v[72:75]
	v_mfma_f32_16x16x32_bf16 v[164:167], v[140:143], v[188:191], v[164:167]
	v_mfma_f32_16x16x32_bf16 v[160:163], v[156:159], v[188:191], v[160:163]
	v_mfma_f32_16x16x32_bf16 v[136:139], v[140:143], v[196:199], v[136:139]
	v_mfma_f32_16x16x32_bf16 v[132:135], v[156:159], v[196:199], v[132:135]
	v_mfma_f32_16x16x32_bf16 v[116:119], v[140:143], v[204:207], v[116:119]
	v_mfma_f32_16x16x32_bf16 v[112:115], v[156:159], v[204:207], v[112:115]
	s_waitcnt lgkmcnt(0)
	v_mfma_f32_16x16x32_bf16 v[76:79], v[140:143], v[228:231], v[76:79]
	v_mfma_f32_16x16x32_bf16 v[72:75], v[156:159], v[228:231], v[72:75]
	s_setprio 1
	s_setprio 0
	v_mfma_f32_16x16x32_bf16 v[148:151], v[168:171], v[184:187], v[148:151]
	v_mfma_f32_16x16x32_bf16 v[144:147], v[176:179], v[184:187], v[144:147]
	v_mfma_f32_16x16x32_bf16 v[124:127], v[168:171], v[192:195], v[124:127]
	v_mfma_f32_16x16x32_bf16 v[120:123], v[176:179], v[192:195], v[120:123]
	v_mfma_f32_16x16x32_bf16 v[108:111], v[168:171], v[200:203], v[108:111]
	v_mfma_f32_16x16x32_bf16 v[104:107], v[176:179], v[200:203], v[104:107]
	v_mfma_f32_16x16x32_bf16 v[68:71], v[168:171], v[224:227], v[68:71]
	v_mfma_f32_16x16x32_bf16 v[64:67], v[176:179], v[224:227], v[64:67]
	v_mfma_f32_16x16x32_bf16 v[148:151], v[172:175], v[188:191], v[148:151]
	v_mfma_f32_16x16x32_bf16 v[144:147], v[180:183], v[188:191], v[144:147]
	v_mfma_f32_16x16x32_bf16 v[124:127], v[172:175], v[196:199], v[124:127]
	v_mfma_f32_16x16x32_bf16 v[120:123], v[180:183], v[196:199], v[120:123]
	v_mfma_f32_16x16x32_bf16 v[108:111], v[172:175], v[204:207], v[108:111]
	v_mfma_f32_16x16x32_bf16 v[104:107], v[180:183], v[204:207], v[104:107]
	v_mfma_f32_16x16x32_bf16 v[68:71], v[172:175], v[228:231], v[68:71]
	v_mfma_f32_16x16x32_bf16 v[64:67], v[180:183], v[228:231], v[64:67]
	s_setprio 1
	s_barrier
	ds_read_b128 v[184:187], v223 offset:16384
	ds_read_b128 v[188:191], v223 offset:17408
	ds_read_b128 v[192:195], v223 offset:18432
	ds_read_b128 v[196:199], v223 offset:19456
	ds_read_b128 v[200:203], v223 offset:20480
	ds_read_b128 v[204:207], v223 offset:21504
	ds_read_b128 v[224:227], v223 offset:22528
	ds_read_b128 v[228:231], v223 offset:23552
	s_mov_b32 m0, s55
	s_nop 0
	buffer_load_dwordx4 v220, s[48:51], s12 offen lds
	s_add_i32 s14, s12, 0x80000
	s_mov_b32 m0, s76
	s_nop 0
	buffer_load_dwordx4 v221, s[48:51], s12 offen lds
	s_nop 0
	s_mov_b32 m0, s77
	s_nop 0
	buffer_load_dwordx4 v220, s[48:51], s14 offen lds
	s_nop 0
	s_mov_b32 m0, s78
	s_nop 0
	buffer_load_dwordx4 v221, s[48:51], s14 offen lds
	s_nop 0
	s_mov_b32 m0, s31
	s_nop 0
	buffer_load_dwordx4 v220, s[64:67], s13 offen lds
	s_nop 0
	s_mov_b32 m0, s79
	s_nop 0
	buffer_load_dwordx4 v221, s[64:67], s13 offen lds
	s_waitcnt vmcnt(8)
	s_waitcnt lgkmcnt(0)
	s_barrier
	s_setprio 0
	s_waitcnt lgkmcnt(7)
	v_mfma_f32_16x16x32_bf16 v[60:63], v[128:131], v[184:187], v[60:63]
	v_mfma_f32_16x16x32_bf16 v[56:59], v[152:155], v[184:187], v[56:59]
	s_waitcnt lgkmcnt(5)
	v_mfma_f32_16x16x32_bf16 v[44:47], v[128:131], v[192:195], v[44:47]
	v_mfma_f32_16x16x32_bf16 v[40:43], v[152:155], v[192:195], v[40:43]
	s_waitcnt lgkmcnt(3)
	v_mfma_f32_16x16x32_bf16 v[28:31], v[128:131], v[200:203], v[28:31]
	v_mfma_f32_16x16x32_bf16 v[24:27], v[152:155], v[200:203], v[24:27]
	s_waitcnt lgkmcnt(1)
	v_mfma_f32_16x16x32_bf16 v[12:15], v[128:131], v[224:227], v[12:15]
	v_mfma_f32_16x16x32_bf16 v[8:11], v[152:155], v[224:227], v[8:11]
	v_mfma_f32_16x16x32_bf16 v[60:63], v[140:143], v[188:191], v[60:63]
	v_mfma_f32_16x16x32_bf16 v[56:59], v[156:159], v[188:191], v[56:59]
	v_mfma_f32_16x16x32_bf16 v[44:47], v[140:143], v[196:199], v[44:47]
	v_mfma_f32_16x16x32_bf16 v[40:43], v[156:159], v[196:199], v[40:43]
	v_mfma_f32_16x16x32_bf16 v[28:31], v[140:143], v[204:207], v[28:31]
	v_mfma_f32_16x16x32_bf16 v[24:27], v[156:159], v[204:207], v[24:27]
	s_waitcnt lgkmcnt(0)
	v_mfma_f32_16x16x32_bf16 v[12:15], v[140:143], v[228:231], v[12:15]
	v_mfma_f32_16x16x32_bf16 v[8:11], v[156:159], v[228:231], v[8:11]
	s_setprio 1
	s_setprio 0
	v_mfma_f32_16x16x32_bf16 v[52:55], v[168:171], v[184:187], v[52:55]
	v_mfma_f32_16x16x32_bf16 v[48:51], v[176:179], v[184:187], v[48:51]
	v_mfma_f32_16x16x32_bf16 v[36:39], v[168:171], v[192:195], v[36:39]
	v_mfma_f32_16x16x32_bf16 v[32:35], v[176:179], v[192:195], v[32:35]
	v_mfma_f32_16x16x32_bf16 v[20:23], v[168:171], v[200:203], v[20:23]
	v_mfma_f32_16x16x32_bf16 v[16:19], v[176:179], v[200:203], v[16:19]
	v_mfma_f32_16x16x32_bf16 v[4:7], v[168:171], v[224:227], v[4:7]
	v_mfma_f32_16x16x32_bf16 v[0:3], v[176:179], v[224:227], v[0:3]
	v_mfma_f32_16x16x32_bf16 v[52:55], v[172:175], v[188:191], v[52:55]
	v_mfma_f32_16x16x32_bf16 v[48:51], v[180:183], v[188:191], v[48:51]
	v_mfma_f32_16x16x32_bf16 v[36:39], v[172:175], v[196:199], v[36:39]
	v_mfma_f32_16x16x32_bf16 v[32:35], v[180:183], v[196:199], v[32:35]
	v_mfma_f32_16x16x32_bf16 v[20:23], v[172:175], v[204:207], v[20:23]
	v_mfma_f32_16x16x32_bf16 v[16:19], v[180:183], v[204:207], v[16:19]
	v_mfma_f32_16x16x32_bf16 v[4:7], v[172:175], v[228:231], v[4:7]
	v_mfma_f32_16x16x32_bf16 v[0:3], v[180:183], v[228:231], v[0:3]
	s_setprio 1
	s_barrier
	v_add_u32_e32 v156, 0x18000, v222
	v_add_u32_e32 v180, 0x1c000, v222
	ds_read_b128 v[128:131], v156
	ds_read_b128 v[140:143], v156 offset:1024
	ds_read_b128 v[152:155], v156 offset:2048
	ds_read_b128 v[156:159], v156 offset:3072
	ds_read_b128 v[168:171], v180
	ds_read_b128 v[172:175], v180 offset:1024
	ds_read_b128 v[176:179], v180 offset:2048
	ds_read_b128 v[180:183], v180 offset:3072
	ds_read_b128 v[184:187], v223 offset:32768
	ds_read_b128 v[188:191], v223 offset:33792
	ds_read_b128 v[192:195], v223 offset:34816
	ds_read_b128 v[196:199], v223 offset:35840
	ds_read_b128 v[200:203], v223 offset:36864
	ds_read_b128 v[204:207], v223 offset:37888
	ds_read_b128 v[224:227], v223 offset:38912
	ds_read_b128 v[228:231], v223 offset:39936
	s_add_i32 s13, s13, 0x80000
	s_mov_b32 m0, s82
	s_nop 0
	buffer_load_dwordx4 v220, s[64:67], s13 offen lds
	s_nop 0
	s_mov_b32 m0, s83
	s_nop 0
	buffer_load_dwordx4 v221, s[64:67], s13 offen lds
	s_waitcnt vmcnt(8)
	s_waitcnt lgkmcnt(0)
	s_barrier
	s_setprio 0
	s_waitcnt lgkmcnt(7)
	v_mfma_f32_16x16x32_bf16 v[164:167], v[128:131], v[184:187], v[164:167]
	v_mfma_f32_16x16x32_bf16 v[160:163], v[152:155], v[184:187], v[160:163]
	s_waitcnt lgkmcnt(5)
	v_mfma_f32_16x16x32_bf16 v[136:139], v[128:131], v[192:195], v[136:139]
	v_mfma_f32_16x16x32_bf16 v[132:135], v[152:155], v[192:195], v[132:135]
	s_waitcnt lgkmcnt(3)
	v_mfma_f32_16x16x32_bf16 v[116:119], v[128:131], v[200:203], v[116:119]
	v_mfma_f32_16x16x32_bf16 v[112:115], v[152:155], v[200:203], v[112:115]
	s_waitcnt lgkmcnt(1)
	v_mfma_f32_16x16x32_bf16 v[76:79], v[128:131], v[224:227], v[76:79]
	v_mfma_f32_16x16x32_bf16 v[72:75], v[152:155], v[224:227], v[72:75]
	v_mfma_f32_16x16x32_bf16 v[164:167], v[140:143], v[188:191], v[164:167]
	v_mfma_f32_16x16x32_bf16 v[160:163], v[156:159], v[188:191], v[160:163]
	v_mfma_f32_16x16x32_bf16 v[136:139], v[140:143], v[196:199], v[136:139]
	v_mfma_f32_16x16x32_bf16 v[132:135], v[156:159], v[196:199], v[132:135]
	v_mfma_f32_16x16x32_bf16 v[116:119], v[140:143], v[204:207], v[116:119]
	v_mfma_f32_16x16x32_bf16 v[112:115], v[156:159], v[204:207], v[112:115]
	s_waitcnt lgkmcnt(0)
	v_mfma_f32_16x16x32_bf16 v[76:79], v[140:143], v[228:231], v[76:79]
	v_mfma_f32_16x16x32_bf16 v[72:75], v[156:159], v[228:231], v[72:75]
	s_setprio 1
	s_setprio 0
	v_mfma_f32_16x16x32_bf16 v[148:151], v[168:171], v[184:187], v[148:151]
	v_mfma_f32_16x16x32_bf16 v[144:147], v[176:179], v[184:187], v[144:147]
	v_mfma_f32_16x16x32_bf16 v[124:127], v[168:171], v[192:195], v[124:127]
	v_mfma_f32_16x16x32_bf16 v[120:123], v[176:179], v[192:195], v[120:123]
	v_mfma_f32_16x16x32_bf16 v[108:111], v[168:171], v[200:203], v[108:111]
	v_mfma_f32_16x16x32_bf16 v[104:107], v[176:179], v[200:203], v[104:107]
	v_mfma_f32_16x16x32_bf16 v[68:71], v[168:171], v[224:227], v[68:71]
	v_mfma_f32_16x16x32_bf16 v[64:67], v[176:179], v[224:227], v[64:67]
	v_mfma_f32_16x16x32_bf16 v[148:151], v[172:175], v[188:191], v[148:151]
	v_mfma_f32_16x16x32_bf16 v[144:147], v[180:183], v[188:191], v[144:147]
	v_mfma_f32_16x16x32_bf16 v[124:127], v[172:175], v[196:199], v[124:127]
	v_mfma_f32_16x16x32_bf16 v[120:123], v[180:183], v[196:199], v[120:123]
	v_mfma_f32_16x16x32_bf16 v[108:111], v[172:175], v[204:207], v[108:111]
	v_mfma_f32_16x16x32_bf16 v[104:107], v[180:183], v[204:207], v[104:107]
	v_mfma_f32_16x16x32_bf16 v[68:71], v[172:175], v[228:231], v[68:71]
	v_mfma_f32_16x16x32_bf16 v[64:67], v[180:183], v[228:231], v[64:67]
	s_setprio 1
	s_barrier
	ds_read_b128 v[184:187], v223 offset:49152
	ds_read_b128 v[188:191], v223 offset:50176
	ds_read_b128 v[192:195], v223 offset:51200
	ds_read_b128 v[196:199], v223 offset:52224
	ds_read_b128 v[200:203], v223 offset:53248
	ds_read_b128 v[204:207], v223 offset:54272
	ds_read_b128 v[224:227], v223 offset:55296
	ds_read_b128 v[228:231], v223 offset:56320
	s_or_b32 s13, s12, 0x4000
	s_mov_b32 m0, s34
	s_nop 0
	buffer_load_dwordx4 v220, s[48:51], s13 offen lds
	s_add_i32 s12, s12, 0x84000
	s_mov_b32 m0, s84
	s_nop 0
	buffer_load_dwordx4 v221, s[48:51], s13 offen lds
	s_nop 0
	s_mov_b32 m0, s87
	s_nop 0
	buffer_load_dwordx4 v220, s[48:51], s12 offen lds
	s_nop 0
	s_mov_b32 m0, s88
	s_nop 0
	buffer_load_dwordx4 v221, s[48:51], s12 offen lds
	s_nop 0
	s_mov_b32 m0, s85
	s_nop 0
	buffer_load_dwordx4 v220, s[64:67], s11 offen lds
	s_nop 0
	s_mov_b32 m0, s86
	s_nop 0
	buffer_load_dwordx4 v221, s[64:67], s11 offen lds
	s_waitcnt vmcnt(8)
	s_waitcnt lgkmcnt(0)
	s_barrier
	s_setprio 0
	s_waitcnt lgkmcnt(7)
	v_mfma_f32_16x16x32_bf16 v[60:63], v[128:131], v[184:187], v[60:63]
	v_mfma_f32_16x16x32_bf16 v[56:59], v[152:155], v[184:187], v[56:59]
	s_waitcnt lgkmcnt(5)
	v_mfma_f32_16x16x32_bf16 v[44:47], v[128:131], v[192:195], v[44:47]
	v_mfma_f32_16x16x32_bf16 v[40:43], v[152:155], v[192:195], v[40:43]
	s_waitcnt lgkmcnt(3)
	v_mfma_f32_16x16x32_bf16 v[28:31], v[128:131], v[200:203], v[28:31]
	v_mfma_f32_16x16x32_bf16 v[24:27], v[152:155], v[200:203], v[24:27]
	s_waitcnt lgkmcnt(1)
	v_mfma_f32_16x16x32_bf16 v[12:15], v[128:131], v[224:227], v[12:15]
	v_mfma_f32_16x16x32_bf16 v[8:11], v[152:155], v[224:227], v[8:11]
	v_mfma_f32_16x16x32_bf16 v[60:63], v[140:143], v[188:191], v[60:63]
	v_mfma_f32_16x16x32_bf16 v[56:59], v[156:159], v[188:191], v[56:59]
	v_mfma_f32_16x16x32_bf16 v[44:47], v[140:143], v[196:199], v[44:47]
	v_mfma_f32_16x16x32_bf16 v[40:43], v[156:159], v[196:199], v[40:43]
	v_mfma_f32_16x16x32_bf16 v[28:31], v[140:143], v[204:207], v[28:31]
	v_mfma_f32_16x16x32_bf16 v[24:27], v[156:159], v[204:207], v[24:27]
	s_waitcnt lgkmcnt(0)
	v_mfma_f32_16x16x32_bf16 v[12:15], v[140:143], v[228:231], v[12:15]
	v_mfma_f32_16x16x32_bf16 v[8:11], v[156:159], v[228:231], v[8:11]
	s_setprio 1
	s_setprio 0
	v_mfma_f32_16x16x32_bf16 v[52:55], v[168:171], v[184:187], v[52:55]
	v_mfma_f32_16x16x32_bf16 v[48:51], v[176:179], v[184:187], v[48:51]
	v_mfma_f32_16x16x32_bf16 v[36:39], v[168:171], v[192:195], v[36:39]
	v_mfma_f32_16x16x32_bf16 v[32:35], v[176:179], v[192:195], v[32:35]
	v_mfma_f32_16x16x32_bf16 v[20:23], v[168:171], v[200:203], v[20:23]
	v_mfma_f32_16x16x32_bf16 v[16:19], v[176:179], v[200:203], v[16:19]
	v_mfma_f32_16x16x32_bf16 v[4:7], v[168:171], v[224:227], v[4:7]
	v_mfma_f32_16x16x32_bf16 v[0:3], v[176:179], v[224:227], v[0:3]
	v_mfma_f32_16x16x32_bf16 v[52:55], v[172:175], v[188:191], v[52:55]
	v_mfma_f32_16x16x32_bf16 v[48:51], v[180:183], v[188:191], v[48:51]
	v_mfma_f32_16x16x32_bf16 v[36:39], v[172:175], v[196:199], v[36:39]
	v_mfma_f32_16x16x32_bf16 v[32:35], v[180:183], v[196:199], v[32:35]
	v_mfma_f32_16x16x32_bf16 v[20:23], v[172:175], v[204:207], v[20:23]
	v_mfma_f32_16x16x32_bf16 v[16:19], v[180:183], v[204:207], v[16:19]
	v_mfma_f32_16x16x32_bf16 v[4:7], v[172:175], v[228:231], v[4:7]
	v_mfma_f32_16x16x32_bf16 v[0:3], v[180:183], v[228:231], v[0:3]
	s_setprio 1
	s_barrier
	s_add_i32 s10, s10, 2
	s_add_i32 s8, s8, 0x8000
	s_add_i32 s9, s9, 0x8000
	s_cmp_gt_u32 s10, 29
	s_cbranch_scc0 .LBB0_691

.Lnb_p5:
	s_add_i32 s53, s37, 0xfff84000
	s_cmp_eq_u32 s52, 28
	s_cselect_b32 s56, s4, s53
	s_cselect_b32 s55, s5, s51
	s_or_b32 s53, s56, 0x4000
	s_mov_b32 m0, s41
	s_nop 0
	buffer_load_dwordx4 v166, s[24:27], s37 offen lds
	s_nop 0
	s_mov_b32 m0, s42
	s_nop 0
	buffer_load_dwordx4 v167, s[24:27], s37 offen lds
	s_waitcnt vmcnt(24)
	s_waitcnt lgkmcnt(0)
	s_barrier
	s_setprio 0
	s_waitcnt lgkmcnt(7)
	v_mfma_f32_16x16x32_bf16 v[148:151], v[152:155], v[190:193], 0
	v_mfma_f32_16x16x32_bf16 v[140:143], v[160:163], v[190:193], 0
	s_waitcnt lgkmcnt(5)
	v_mfma_f32_16x16x32_bf16 v[132:135], v[152:155], v[198:201], 0
	v_mfma_f32_16x16x32_bf16 v[124:127], v[160:163], v[198:201], 0
	s_waitcnt lgkmcnt(3)
	v_mfma_f32_16x16x32_bf16 v[116:119], v[152:155], v[220:223], 0
	v_mfma_f32_16x16x32_bf16 v[108:111], v[160:163], v[220:223], 0
	s_waitcnt lgkmcnt(1)
	v_mfma_f32_16x16x32_bf16 v[76:79], v[152:155], v[228:231], 0
	v_mfma_f32_16x16x32_bf16 v[68:71], v[160:163], v[228:231], 0
	v_mfma_f32_16x16x32_bf16 v[148:151], v[156:159], v[194:197], v[148:151]
	v_mfma_f32_16x16x32_bf16 v[140:143], v[170:173], v[194:197], v[140:143]
	v_mfma_f32_16x16x32_bf16 v[132:135], v[156:159], v[202:205], v[132:135]
	v_mfma_f32_16x16x32_bf16 v[124:127], v[170:173], v[202:205], v[124:127]
	v_mfma_f32_16x16x32_bf16 v[116:119], v[156:159], v[224:227], v[116:119]
	v_mfma_f32_16x16x32_bf16 v[108:111], v[170:173], v[224:227], v[108:111]
	s_waitcnt lgkmcnt(0)
	v_mfma_f32_16x16x32_bf16 v[76:79], v[156:159], v[240:243], v[76:79]
	v_mfma_f32_16x16x32_bf16 v[68:71], v[170:173], v[240:243], v[68:71]
	s_setprio 1
	s_setprio 0
	v_mfma_f32_16x16x32_bf16 v[144:147], v[174:177], v[190:193], 0
	v_mfma_f32_16x16x32_bf16 v[136:139], v[182:185], v[190:193], 0
	v_mfma_f32_16x16x32_bf16 v[128:131], v[174:177], v[198:201], 0
	v_mfma_f32_16x16x32_bf16 v[120:123], v[182:185], v[198:201], 0
	v_mfma_f32_16x16x32_bf16 v[112:115], v[174:177], v[220:223], 0
	v_mfma_f32_16x16x32_bf16 v[104:107], v[182:185], v[220:223], 0
	v_mfma_f32_16x16x32_bf16 v[72:75], v[174:177], v[228:231], 0
	v_mfma_f32_16x16x32_bf16 v[64:67], v[182:185], v[228:231], 0
	v_mfma_f32_16x16x32_bf16 v[144:147], v[178:181], v[194:197], v[144:147]
	v_mfma_f32_16x16x32_bf16 v[136:139], v[186:189], v[194:197], v[136:139]
	v_mfma_f32_16x16x32_bf16 v[128:131], v[178:181], v[202:205], v[128:131]
	v_mfma_f32_16x16x32_bf16 v[120:123], v[186:189], v[202:205], v[120:123]
	v_mfma_f32_16x16x32_bf16 v[112:115], v[178:181], v[224:227], v[112:115]
	v_mfma_f32_16x16x32_bf16 v[104:107], v[186:189], v[224:227], v[104:107]
	v_mfma_f32_16x16x32_bf16 v[72:75], v[178:181], v[240:243], v[72:75]
	v_mfma_f32_16x16x32_bf16 v[64:67], v[186:189], v[240:243], v[64:67]
	s_setprio 1
	s_barrier
	ds_read_b128 v[190:193], v169 offset:16384
	ds_read_b128 v[194:197], v169 offset:17408
	ds_read_b128 v[198:201], v169 offset:18432
	ds_read_b128 v[202:205], v169 offset:19456
	ds_read_b128 v[220:223], v169 offset:20480
	ds_read_b128 v[224:227], v169 offset:21504
	ds_read_b128 v[228:231], v169 offset:22528
	ds_read_b128 v[240:243], v169 offset:23552
	s_mov_b32 m0, s7
	s_nop 0
	buffer_load_dwordx4 v166, s[28:31], s55 offen lds
	s_add_i32 s57, s55, 0x80000
	s_mov_b32 m0, s8
	s_nop 0
	buffer_load_dwordx4 v167, s[28:31], s55 offen lds
	s_nop 0
	s_mov_b32 m0, s9
	s_nop 0
	buffer_load_dwordx4 v166, s[28:31], s57 offen lds
	s_nop 0
	s_mov_b32 m0, s10
	s_nop 0
	buffer_load_dwordx4 v167, s[28:31], s57 offen lds
	s_nop 0
	s_mov_b32 m0, s6
	s_nop 0
	buffer_load_dwordx4 v166, s[24:27], s56 offen lds
	s_nop 0
	s_mov_b32 m0, s11
	s_nop 0
	buffer_load_dwordx4 v167, s[24:27], s56 offen lds
	s_waitcnt vmcnt(24)
	s_waitcnt lgkmcnt(0)
	s_barrier
	s_setprio 0
	s_waitcnt lgkmcnt(7)
	v_mfma_f32_16x16x32_bf16 v[60:63], v[152:155], v[190:193], 0
	v_mfma_f32_16x16x32_bf16 v[52:55], v[160:163], v[190:193], 0
	s_waitcnt lgkmcnt(5)
	v_mfma_f32_16x16x32_bf16 v[44:47], v[152:155], v[198:201], 0
	v_mfma_f32_16x16x32_bf16 v[36:39], v[160:163], v[198:201], 0
	s_waitcnt lgkmcnt(3)
	v_mfma_f32_16x16x32_bf16 v[28:31], v[152:155], v[220:223], 0
	v_mfma_f32_16x16x32_bf16 v[20:23], v[160:163], v[220:223], 0
	s_waitcnt lgkmcnt(1)
	v_mfma_f32_16x16x32_bf16 v[12:15], v[152:155], v[228:231], 0
	v_mfma_f32_16x16x32_bf16 v[4:7], v[160:163], v[228:231], 0
	v_mfma_f32_16x16x32_bf16 v[60:63], v[156:159], v[194:197], v[60:63]
	v_mfma_f32_16x16x32_bf16 v[52:55], v[170:173], v[194:197], v[52:55]
	v_mfma_f32_16x16x32_bf16 v[44:47], v[156:159], v[202:205], v[44:47]
	v_mfma_f32_16x16x32_bf16 v[36:39], v[170:173], v[202:205], v[36:39]
	v_mfma_f32_16x16x32_bf16 v[28:31], v[156:159], v[224:227], v[28:31]
	v_mfma_f32_16x16x32_bf16 v[20:23], v[170:173], v[224:227], v[20:23]
	s_waitcnt lgkmcnt(0)
	v_mfma_f32_16x16x32_bf16 v[12:15], v[156:159], v[240:243], v[12:15]
	v_mfma_f32_16x16x32_bf16 v[4:7], v[170:173], v[240:243], v[4:7]
	s_setprio 1
	s_setprio 0
	v_mfma_f32_16x16x32_bf16 v[56:59], v[174:177], v[190:193], 0
	v_mfma_f32_16x16x32_bf16 v[48:51], v[182:185], v[190:193], 0
	v_mfma_f32_16x16x32_bf16 v[40:43], v[174:177], v[198:201], 0
	v_mfma_f32_16x16x32_bf16 v[32:35], v[182:185], v[198:201], 0
	v_mfma_f32_16x16x32_bf16 v[24:27], v[174:177], v[220:223], 0
	v_mfma_f32_16x16x32_bf16 v[16:19], v[182:185], v[220:223], 0
	v_mfma_f32_16x16x32_bf16 v[8:11], v[174:177], v[228:231], 0
	v_mfma_f32_16x16x32_bf16 v[0:3], v[182:185], v[228:231], 0
	v_mfma_f32_16x16x32_bf16 v[56:59], v[178:181], v[194:197], v[56:59]
	v_mfma_f32_16x16x32_bf16 v[48:51], v[186:189], v[194:197], v[48:51]
	v_mfma_f32_16x16x32_bf16 v[40:43], v[178:181], v[202:205], v[40:43]
	v_mfma_f32_16x16x32_bf16 v[32:35], v[186:189], v[202:205], v[32:35]
	v_mfma_f32_16x16x32_bf16 v[24:27], v[178:181], v[224:227], v[24:27]
	v_mfma_f32_16x16x32_bf16 v[16:19], v[186:189], v[224:227], v[16:19]
	v_mfma_f32_16x16x32_bf16 v[8:11], v[178:181], v[240:243], v[8:11]
	v_mfma_f32_16x16x32_bf16 v[0:3], v[186:189], v[240:243], v[0:3]
	s_setprio 1
	s_barrier
	v_add_u32_e32 v164, 0x18000, v168
	ds_read_b128 v[152:155], v164
	ds_read_b128 v[156:159], v164 offset:1024
	ds_read_b128 v[160:163], v164 offset:2048
	ds_read_b128 v[170:173], v164 offset:3072
	v_add_u32_e32 v164, 0x1c000, v168
	ds_read_b128 v[174:177], v164
	ds_read_b128 v[178:181], v164 offset:1024
	ds_read_b128 v[182:185], v164 offset:2048
	ds_read_b128 v[186:189], v164 offset:3072
	ds_read_b128 v[190:193], v169 offset:32768
	ds_read_b128 v[194:197], v169 offset:33792
	ds_read_b128 v[198:201], v169 offset:34816
	ds_read_b128 v[202:205], v169 offset:35840
	ds_read_b128 v[220:223], v169 offset:36864
	ds_read_b128 v[224:227], v169 offset:37888
	ds_read_b128 v[228:231], v169 offset:38912
	ds_read_b128 v[240:243], v169 offset:39936
	s_add_i32 s56, s56, 0x80000
	s_mov_b32 m0, s12
	s_nop 0
	buffer_load_dwordx4 v166, s[24:27], s56 offen lds
	s_nop 0
	s_mov_b32 m0, s13
	s_nop 0
	buffer_load_dwordx4 v167, s[24:27], s56 offen lds
	s_waitcnt vmcnt(8)
	s_waitcnt lgkmcnt(0)
	s_barrier
	s_setprio 0
	s_waitcnt lgkmcnt(7)
	v_mfma_f32_16x16x32_bf16 v[148:151], v[152:155], v[190:193], v[148:151]
	v_mfma_f32_16x16x32_bf16 v[140:143], v[160:163], v[190:193], v[140:143]
	s_waitcnt lgkmcnt(5)
	v_mfma_f32_16x16x32_bf16 v[132:135], v[152:155], v[198:201], v[132:135]
	v_mfma_f32_16x16x32_bf16 v[124:127], v[160:163], v[198:201], v[124:127]
	s_waitcnt lgkmcnt(3)
	v_mfma_f32_16x16x32_bf16 v[116:119], v[152:155], v[220:223], v[116:119]
	v_mfma_f32_16x16x32_bf16 v[108:111], v[160:163], v[220:223], v[108:111]
	s_waitcnt lgkmcnt(1)
	v_mfma_f32_16x16x32_bf16 v[76:79], v[152:155], v[228:231], v[76:79]
	v_mfma_f32_16x16x32_bf16 v[68:71], v[160:163], v[228:231], v[68:71]
	v_mfma_f32_16x16x32_bf16 v[148:151], v[156:159], v[194:197], v[148:151]
	v_mfma_f32_16x16x32_bf16 v[140:143], v[170:173], v[194:197], v[140:143]
	v_mfma_f32_16x16x32_bf16 v[132:135], v[156:159], v[202:205], v[132:135]
	v_mfma_f32_16x16x32_bf16 v[124:127], v[170:173], v[202:205], v[124:127]
	v_mfma_f32_16x16x32_bf16 v[116:119], v[156:159], v[224:227], v[116:119]
	v_mfma_f32_16x16x32_bf16 v[108:111], v[170:173], v[224:227], v[108:111]
	s_waitcnt lgkmcnt(0)
	v_mfma_f32_16x16x32_bf16 v[76:79], v[156:159], v[240:243], v[76:79]
	v_mfma_f32_16x16x32_bf16 v[68:71], v[170:173], v[240:243], v[68:71]
	s_setprio 1
	s_setprio 0
	v_mfma_f32_16x16x32_bf16 v[144:147], v[174:177], v[190:193], v[144:147]
	v_mfma_f32_16x16x32_bf16 v[136:139], v[182:185], v[190:193], v[136:139]
	v_mfma_f32_16x16x32_bf16 v[128:131], v[174:177], v[198:201], v[128:131]
	v_mfma_f32_16x16x32_bf16 v[120:123], v[182:185], v[198:201], v[120:123]
	v_mfma_f32_16x16x32_bf16 v[112:115], v[174:177], v[220:223], v[112:115]
	v_mfma_f32_16x16x32_bf16 v[104:107], v[182:185], v[220:223], v[104:107]
	v_mfma_f32_16x16x32_bf16 v[72:75], v[174:177], v[228:231], v[72:75]
	v_mfma_f32_16x16x32_bf16 v[64:67], v[182:185], v[228:231], v[64:67]
	v_mfma_f32_16x16x32_bf16 v[144:147], v[178:181], v[194:197], v[144:147]
	v_mfma_f32_16x16x32_bf16 v[136:139], v[186:189], v[194:197], v[136:139]
	v_mfma_f32_16x16x32_bf16 v[128:131], v[178:181], v[202:205], v[128:131]
	v_mfma_f32_16x16x32_bf16 v[120:123], v[186:189], v[202:205], v[120:123]
	v_mfma_f32_16x16x32_bf16 v[112:115], v[178:181], v[224:227], v[112:115]
	v_mfma_f32_16x16x32_bf16 v[104:107], v[186:189], v[224:227], v[104:107]
	v_mfma_f32_16x16x32_bf16 v[72:75], v[178:181], v[240:243], v[72:75]
	v_mfma_f32_16x16x32_bf16 v[64:67], v[186:189], v[240:243], v[64:67]
	s_setprio 1
	s_barrier
	ds_read_b128 v[190:193], v169 offset:49152
	ds_read_b128 v[194:197], v169 offset:50176
	ds_read_b128 v[198:201], v169 offset:51200
	ds_read_b128 v[202:205], v169 offset:52224
	ds_read_b128 v[220:223], v169 offset:53248
	ds_read_b128 v[224:227], v169 offset:54272
	ds_read_b128 v[228:231], v169 offset:55296
	ds_read_b128 v[240:243], v169 offset:56320
	s_or_b32 s56, s55, 0x4000
	s_mov_b32 m0, s16
	s_nop 0
	buffer_load_dwordx4 v166, s[28:31], s56 offen lds
	s_add_i32 s55, s55, 0x84000
	s_mov_b32 m0, s17
	s_nop 0
	buffer_load_dwordx4 v167, s[28:31], s56 offen lds
	s_nop 0
	s_mov_b32 m0, s34
	s_nop 0
	buffer_load_dwordx4 v166, s[28:31], s55 offen lds
	s_nop 0
	s_mov_b32 m0, s40
	s_nop 0
	buffer_load_dwordx4 v167, s[28:31], s55 offen lds
	s_nop 0
	s_mov_b32 m0, s18
	s_nop 0
	buffer_load_dwordx4 v166, s[24:27], s53 offen lds
	s_nop 0
	s_mov_b32 m0, s19
	s_nop 0
	buffer_load_dwordx4 v167, s[24:27], s53 offen lds
	s_waitcnt vmcnt(8)
	s_waitcnt lgkmcnt(0)
	s_barrier
	s_setprio 0
	s_waitcnt lgkmcnt(7)
	v_mfma_f32_16x16x32_bf16 v[60:63], v[152:155], v[190:193], v[60:63]
	v_mfma_f32_16x16x32_bf16 v[52:55], v[160:163], v[190:193], v[52:55]
	s_waitcnt lgkmcnt(5)
	v_mfma_f32_16x16x32_bf16 v[44:47], v[152:155], v[198:201], v[44:47]
	v_mfma_f32_16x16x32_bf16 v[36:39], v[160:163], v[198:201], v[36:39]
	s_waitcnt lgkmcnt(3)
	v_mfma_f32_16x16x32_bf16 v[28:31], v[152:155], v[220:223], v[28:31]
	v_mfma_f32_16x16x32_bf16 v[20:23], v[160:163], v[220:223], v[20:23]
	s_waitcnt lgkmcnt(1)
	v_mfma_f32_16x16x32_bf16 v[12:15], v[152:155], v[228:231], v[12:15]
	v_mfma_f32_16x16x32_bf16 v[4:7], v[160:163], v[228:231], v[4:7]
	v_mfma_f32_16x16x32_bf16 v[60:63], v[156:159], v[194:197], v[60:63]
	v_mfma_f32_16x16x32_bf16 v[52:55], v[170:173], v[194:197], v[52:55]
	v_mfma_f32_16x16x32_bf16 v[44:47], v[156:159], v[202:205], v[44:47]
	v_mfma_f32_16x16x32_bf16 v[36:39], v[170:173], v[202:205], v[36:39]
	v_mfma_f32_16x16x32_bf16 v[28:31], v[156:159], v[224:227], v[28:31]
	v_mfma_f32_16x16x32_bf16 v[20:23], v[170:173], v[224:227], v[20:23]
	s_waitcnt lgkmcnt(0)
	v_mfma_f32_16x16x32_bf16 v[12:15], v[156:159], v[240:243], v[12:15]
	v_mfma_f32_16x16x32_bf16 v[4:7], v[170:173], v[240:243], v[4:7]
	s_setprio 1
	s_setprio 0
	v_mfma_f32_16x16x32_bf16 v[56:59], v[174:177], v[190:193], v[56:59]
	v_mfma_f32_16x16x32_bf16 v[48:51], v[182:185], v[190:193], v[48:51]
	v_mfma_f32_16x16x32_bf16 v[40:43], v[174:177], v[198:201], v[40:43]
	v_mfma_f32_16x16x32_bf16 v[32:35], v[182:185], v[198:201], v[32:35]
	v_mfma_f32_16x16x32_bf16 v[24:27], v[174:177], v[220:223], v[24:27]
	v_mfma_f32_16x16x32_bf16 v[16:19], v[182:185], v[220:223], v[16:19]
	v_mfma_f32_16x16x32_bf16 v[8:11], v[174:177], v[228:231], v[8:11]
	v_mfma_f32_16x16x32_bf16 v[0:3], v[182:185], v[228:231], v[0:3]
	v_mfma_f32_16x16x32_bf16 v[56:59], v[178:181], v[194:197], v[56:59]
	v_mfma_f32_16x16x32_bf16 v[48:51], v[186:189], v[194:197], v[48:51]
	v_mfma_f32_16x16x32_bf16 v[40:43], v[178:181], v[202:205], v[40:43]
	v_mfma_f32_16x16x32_bf16 v[32:35], v[186:189], v[202:205], v[32:35]
	v_mfma_f32_16x16x32_bf16 v[24:27], v[178:181], v[224:227], v[24:27]
	v_mfma_f32_16x16x32_bf16 v[16:19], v[186:189], v[224:227], v[16:19]
	v_mfma_f32_16x16x32_bf16 v[8:11], v[178:181], v[240:243], v[8:11]
	v_mfma_f32_16x16x32_bf16 v[0:3], v[186:189], v[240:243], v[0:3]
	s_setprio 1
	s_barrier
	s_add_i32 s52, s52, 2
	s_add_i32 s37, s37, 0x8000
	s_add_i32 s51, s51, 0x8000
.LBB0_795:
	v_add_u32_e32 v164, 0x10000, v168
	ds_read_b128 v[152:155], v164
	ds_read_b128 v[156:159], v164 offset:1024
	ds_read_b128 v[160:163], v164 offset:2048
	ds_read_b128 v[170:173], v164 offset:3072
	v_add_u32_e32 v164, 0x14000, v168
	ds_read_b128 v[174:177], v164
	ds_read_b128 v[178:181], v164 offset:1024
	ds_read_b128 v[182:185], v164 offset:2048
	ds_read_b128 v[186:189], v164 offset:3072
	s_add_i32 s53, s37, 0xfff84000
	s_cmp_eq_u32 s52, 28
	s_cselect_b32 s56, s4, s53
	s_cselect_b32 s55, s5, s51
	s_or_b32 s53, s56, 0x4000
	ds_read_b128 v[190:193], v169
	ds_read_b128 v[194:197], v169 offset:1024
	ds_read_b128 v[198:201], v169 offset:2048
	ds_read_b128 v[202:205], v169 offset:3072
	ds_read_b128 v[220:223], v169 offset:4096
	ds_read_b128 v[224:227], v169 offset:5120
	ds_read_b128 v[228:231], v169 offset:6144
	ds_read_b128 v[240:243], v169 offset:7168
	s_mov_b32 m0, s41
	s_nop 0
	buffer_load_dwordx4 v166, s[24:27], s37 offen lds
	s_nop 0
	s_mov_b32 m0, s42
	s_nop 0
	buffer_load_dwordx4 v167, s[24:27], s37 offen lds
	s_waitcnt vmcnt(8)
	s_waitcnt lgkmcnt(0)
	s_barrier
	s_setprio 0
	s_waitcnt lgkmcnt(7)
	v_mfma_f32_16x16x32_bf16 v[148:151], v[152:155], v[190:193], v[148:151]
	v_mfma_f32_16x16x32_bf16 v[140:143], v[160:163], v[190:193], v[140:143]
	s_waitcnt lgkmcnt(5)
	v_mfma_f32_16x16x32_bf16 v[132:135], v[152:155], v[198:201], v[132:135]
	v_mfma_f32_16x16x32_bf16 v[124:127], v[160:163], v[198:201], v[124:127]
	s_waitcnt lgkmcnt(3)
	v_mfma_f32_16x16x32_bf16 v[116:119], v[152:155], v[220:223], v[116:119]
	v_mfma_f32_16x16x32_bf16 v[108:111], v[160:163], v[220:223], v[108:111]
	s_waitcnt lgkmcnt(1)
	v_mfma_f32_16x16x32_bf16 v[76:79], v[152:155], v[228:231], v[76:79]
	v_mfma_f32_16x16x32_bf16 v[68:71], v[160:163], v[228:231], v[68:71]
	v_mfma_f32_16x16x32_bf16 v[148:151], v[156:159], v[194:197], v[148:151]
	v_mfma_f32_16x16x32_bf16 v[140:143], v[170:173], v[194:197], v[140:143]
	v_mfma_f32_16x16x32_bf16 v[132:135], v[156:159], v[202:205], v[132:135]
	v_mfma_f32_16x16x32_bf16 v[124:127], v[170:173], v[202:205], v[124:127]
	v_mfma_f32_16x16x32_bf16 v[116:119], v[156:159], v[224:227], v[116:119]
	v_mfma_f32_16x16x32_bf16 v[108:111], v[170:173], v[224:227], v[108:111]
	s_waitcnt lgkmcnt(0)
	v_mfma_f32_16x16x32_bf16 v[76:79], v[156:159], v[240:243], v[76:79]
	v_mfma_f32_16x16x32_bf16 v[68:71], v[170:173], v[240:243], v[68:71]
	s_setprio 1
	s_setprio 0
	v_mfma_f32_16x16x32_bf16 v[144:147], v[174:177], v[190:193], v[144:147]
	v_mfma_f32_16x16x32_bf16 v[136:139], v[182:185], v[190:193], v[136:139]
	v_mfma_f32_16x16x32_bf16 v[128:131], v[174:177], v[198:201], v[128:131]
	v_mfma_f32_16x16x32_bf16 v[120:123], v[182:185], v[198:201], v[120:123]
	v_mfma_f32_16x16x32_bf16 v[112:115], v[174:177], v[220:223], v[112:115]
	v_mfma_f32_16x16x32_bf16 v[104:107], v[182:185], v[220:223], v[104:107]
	v_mfma_f32_16x16x32_bf16 v[72:75], v[174:177], v[228:231], v[72:75]
	v_mfma_f32_16x16x32_bf16 v[64:67], v[182:185], v[228:231], v[64:67]
	v_mfma_f32_16x16x32_bf16 v[144:147], v[178:181], v[194:197], v[144:147]
	v_mfma_f32_16x16x32_bf16 v[136:139], v[186:189], v[194:197], v[136:139]
	v_mfma_f32_16x16x32_bf16 v[128:131], v[178:181], v[202:205], v[128:131]
	v_mfma_f32_16x16x32_bf16 v[120:123], v[186:189], v[202:205], v[120:123]
	v_mfma_f32_16x16x32_bf16 v[112:115], v[178:181], v[224:227], v[112:115]
	v_mfma_f32_16x16x32_bf16 v[104:107], v[186:189], v[224:227], v[104:107]
	v_mfma_f32_16x16x32_bf16 v[72:75], v[178:181], v[240:243], v[72:75]
	v_mfma_f32_16x16x32_bf16 v[64:67], v[186:189], v[240:243], v[64:67]
	s_setprio 1
	s_barrier
	ds_read_b128 v[190:193], v169 offset:16384
	ds_read_b128 v[194:197], v169 offset:17408
	ds_read_b128 v[198:201], v169 offset:18432
	ds_read_b128 v[202:205], v169 offset:19456
	ds_read_b128 v[220:223], v169 offset:20480
	ds_read_b128 v[224:227], v169 offset:21504
	ds_read_b128 v[228:231], v169 offset:22528
	ds_read_b128 v[240:243], v169 offset:23552
	s_mov_b32 m0, s7
	s_nop 0
	buffer_load_dwordx4 v166, s[28:31], s55 offen lds
	s_add_i32 s57, s55, 0x80000
	s_mov_b32 m0, s8
	s_nop 0
	buffer_load_dwordx4 v167, s[28:31], s55 offen lds
	s_nop 0
	s_mov_b32 m0, s9
	s_nop 0
	buffer_load_dwordx4 v166, s[28:31], s57 offen lds
	s_nop 0
	s_mov_b32 m0, s10
	s_nop 0
	buffer_load_dwordx4 v167, s[28:31], s57 offen lds
	s_nop 0
	s_mov_b32 m0, s6
	s_nop 0
	buffer_load_dwordx4 v166, s[24:27], s56 offen lds
	s_nop 0
	s_mov_b32 m0, s11
	s_nop 0
	buffer_load_dwordx4 v167, s[24:27], s56 offen lds
	s_waitcnt vmcnt(8)
	s_waitcnt lgkmcnt(0)
	s_barrier
	s_setprio 0
	s_waitcnt lgkmcnt(7)
	v_mfma_f32_16x16x32_bf16 v[60:63], v[152:155], v[190:193], v[60:63]
	v_mfma_f32_16x16x32_bf16 v[52:55], v[160:163], v[190:193], v[52:55]
	s_waitcnt lgkmcnt(5)
	v_mfma_f32_16x16x32_bf16 v[44:47], v[152:155], v[198:201], v[44:47]
	v_mfma_f32_16x16x32_bf16 v[36:39], v[160:163], v[198:201], v[36:39]
	s_waitcnt lgkmcnt(3)
	v_mfma_f32_16x16x32_bf16 v[28:31], v[152:155], v[220:223], v[28:31]
	v_mfma_f32_16x16x32_bf16 v[20:23], v[160:163], v[220:223], v[20:23]
	s_waitcnt lgkmcnt(1)
	v_mfma_f32_16x16x32_bf16 v[12:15], v[152:155], v[228:231], v[12:15]
	v_mfma_f32_16x16x32_bf16 v[4:7], v[160:163], v[228:231], v[4:7]
	v_mfma_f32_16x16x32_bf16 v[60:63], v[156:159], v[194:197], v[60:63]
	v_mfma_f32_16x16x32_bf16 v[52:55], v[170:173], v[194:197], v[52:55]
	v_mfma_f32_16x16x32_bf16 v[44:47], v[156:159], v[202:205], v[44:47]
	v_mfma_f32_16x16x32_bf16 v[36:39], v[170:173], v[202:205], v[36:39]
	v_mfma_f32_16x16x32_bf16 v[28:31], v[156:159], v[224:227], v[28:31]
	v_mfma_f32_16x16x32_bf16 v[20:23], v[170:173], v[224:227], v[20:23]
	s_waitcnt lgkmcnt(0)
	v_mfma_f32_16x16x32_bf16 v[12:15], v[156:159], v[240:243], v[12:15]
	v_mfma_f32_16x16x32_bf16 v[4:7], v[170:173], v[240:243], v[4:7]
	s_setprio 1
	s_setprio 0
	v_mfma_f32_16x16x32_bf16 v[56:59], v[174:177], v[190:193], v[56:59]
	v_mfma_f32_16x16x32_bf16 v[48:51], v[182:185], v[190:193], v[48:51]
	v_mfma_f32_16x16x32_bf16 v[40:43], v[174:177], v[198:201], v[40:43]
	v_mfma_f32_16x16x32_bf16 v[32:35], v[182:185], v[198:201], v[32:35]
	v_mfma_f32_16x16x32_bf16 v[24:27], v[174:177], v[220:223], v[24:27]
	v_mfma_f32_16x16x32_bf16 v[16:19], v[182:185], v[220:223], v[16:19]
	v_mfma_f32_16x16x32_bf16 v[8:11], v[174:177], v[228:231], v[8:11]
	v_mfma_f32_16x16x32_bf16 v[0:3], v[182:185], v[228:231], v[0:3]
	v_mfma_f32_16x16x32_bf16 v[56:59], v[178:181], v[194:197], v[56:59]
	v_mfma_f32_16x16x32_bf16 v[48:51], v[186:189], v[194:197], v[48:51]
	v_mfma_f32_16x16x32_bf16 v[40:43], v[178:181], v[202:205], v[40:43]
	v_mfma_f32_16x16x32_bf16 v[32:35], v[186:189], v[202:205], v[32:35]
	v_mfma_f32_16x16x32_bf16 v[24:27], v[178:181], v[224:227], v[24:27]
	v_mfma_f32_16x16x32_bf16 v[16:19], v[186:189], v[224:227], v[16:19]
	v_mfma_f32_16x16x32_bf16 v[8:11], v[178:181], v[240:243], v[8:11]
	v_mfma_f32_16x16x32_bf16 v[0:3], v[186:189], v[240:243], v[0:3]
	s_setprio 1
	s_barrier
	v_add_u32_e32 v164, 0x18000, v168
	ds_read_b128 v[152:155], v164
	ds_read_b128 v[156:159], v164 offset:1024
	ds_read_b128 v[160:163], v164 offset:2048
	ds_read_b128 v[170:173], v164 offset:3072
	v_add_u32_e32 v164, 0x1c000, v168
	ds_read_b128 v[174:177], v164
	ds_read_b128 v[178:181], v164 offset:1024
	ds_read_b128 v[182:185], v164 offset:2048
	ds_read_b128 v[186:189], v164 offset:3072
	ds_read_b128 v[190:193], v169 offset:32768
	ds_read_b128 v[194:197], v169 offset:33792
	ds_read_b128 v[198:201], v169 offset:34816
	ds_read_b128 v[202:205], v169 offset:35840
	ds_read_b128 v[220:223], v169 offset:36864
	ds_read_b128 v[224:227], v169 offset:37888
	ds_read_b128 v[228:231], v169 offset:38912
	ds_read_b128 v[240:243], v169 offset:39936
	s_add_i32 s56, s56, 0x80000
	s_mov_b32 m0, s12
	s_nop 0
	buffer_load_dwordx4 v166, s[24:27], s56 offen lds
	s_nop 0
	s_mov_b32 m0, s13
	s_nop 0
	buffer_load_dwordx4 v167, s[24:27], s56 offen lds
	s_waitcnt vmcnt(8)
	s_waitcnt lgkmcnt(0)
	s_barrier
	s_setprio 0
	s_waitcnt lgkmcnt(7)
	v_mfma_f32_16x16x32_bf16 v[148:151], v[152:155], v[190:193], v[148:151]
	v_mfma_f32_16x16x32_bf16 v[140:143], v[160:163], v[190:193], v[140:143]
	s_waitcnt lgkmcnt(5)
	v_mfma_f32_16x16x32_bf16 v[132:135], v[152:155], v[198:201], v[132:135]
	v_mfma_f32_16x16x32_bf16 v[124:127], v[160:163], v[198:201], v[124:127]
	s_waitcnt lgkmcnt(3)
	v_mfma_f32_16x16x32_bf16 v[116:119], v[152:155], v[220:223], v[116:119]
	v_mfma_f32_16x16x32_bf16 v[108:111], v[160:163], v[220:223], v[108:111]
	s_waitcnt lgkmcnt(1)
	v_mfma_f32_16x16x32_bf16 v[76:79], v[152:155], v[228:231], v[76:79]
	v_mfma_f32_16x16x32_bf16 v[68:71], v[160:163], v[228:231], v[68:71]
	v_mfma_f32_16x16x32_bf16 v[148:151], v[156:159], v[194:197], v[148:151]
	v_mfma_f32_16x16x32_bf16 v[140:143], v[170:173], v[194:197], v[140:143]
	v_mfma_f32_16x16x32_bf16 v[132:135], v[156:159], v[202:205], v[132:135]
	v_mfma_f32_16x16x32_bf16 v[124:127], v[170:173], v[202:205], v[124:127]
	v_mfma_f32_16x16x32_bf16 v[116:119], v[156:159], v[224:227], v[116:119]
	v_mfma_f32_16x16x32_bf16 v[108:111], v[170:173], v[224:227], v[108:111]
	s_waitcnt lgkmcnt(0)
	v_mfma_f32_16x16x32_bf16 v[76:79], v[156:159], v[240:243], v[76:79]
	v_mfma_f32_16x16x32_bf16 v[68:71], v[170:173], v[240:243], v[68:71]
	s_setprio 1
	s_setprio 0
	v_mfma_f32_16x16x32_bf16 v[144:147], v[174:177], v[190:193], v[144:147]
	v_mfma_f32_16x16x32_bf16 v[136:139], v[182:185], v[190:193], v[136:139]
	v_mfma_f32_16x16x32_bf16 v[128:131], v[174:177], v[198:201], v[128:131]
	v_mfma_f32_16x16x32_bf16 v[120:123], v[182:185], v[198:201], v[120:123]
	v_mfma_f32_16x16x32_bf16 v[112:115], v[174:177], v[220:223], v[112:115]
	v_mfma_f32_16x16x32_bf16 v[104:107], v[182:185], v[220:223], v[104:107]
	v_mfma_f32_16x16x32_bf16 v[72:75], v[174:177], v[228:231], v[72:75]
	v_mfma_f32_16x16x32_bf16 v[64:67], v[182:185], v[228:231], v[64:67]
	v_mfma_f32_16x16x32_bf16 v[144:147], v[178:181], v[194:197], v[144:147]
	v_mfma_f32_16x16x32_bf16 v[136:139], v[186:189], v[194:197], v[136:139]
	v_mfma_f32_16x16x32_bf16 v[128:131], v[178:181], v[202:205], v[128:131]
	v_mfma_f32_16x16x32_bf16 v[120:123], v[186:189], v[202:205], v[120:123]
	v_mfma_f32_16x16x32_bf16 v[112:115], v[178:181], v[224:227], v[112:115]
	v_mfma_f32_16x16x32_bf16 v[104:107], v[186:189], v[224:227], v[104:107]
	v_mfma_f32_16x16x32_bf16 v[72:75], v[178:181], v[240:243], v[72:75]
	v_mfma_f32_16x16x32_bf16 v[64:67], v[186:189], v[240:243], v[64:67]
	s_setprio 1
	s_barrier
	ds_read_b128 v[190:193], v169 offset:49152
	ds_read_b128 v[194:197], v169 offset:50176
	ds_read_b128 v[198:201], v169 offset:51200
	ds_read_b128 v[202:205], v169 offset:52224
	ds_read_b128 v[220:223], v169 offset:53248
	ds_read_b128 v[224:227], v169 offset:54272
	ds_read_b128 v[228:231], v169 offset:55296
	ds_read_b128 v[240:243], v169 offset:56320
	s_or_b32 s56, s55, 0x4000
	s_mov_b32 m0, s16
	s_nop 0
	buffer_load_dwordx4 v166, s[28:31], s56 offen lds
	s_add_i32 s55, s55, 0x84000
	s_mov_b32 m0, s17
	s_nop 0
	buffer_load_dwordx4 v167, s[28:31], s56 offen lds
	s_nop 0
	s_mov_b32 m0, s34
	s_nop 0
	buffer_load_dwordx4 v166, s[28:31], s55 offen lds
	s_nop 0
	s_mov_b32 m0, s40
	s_nop 0
	buffer_load_dwordx4 v167, s[28:31], s55 offen lds
	s_nop 0
	s_mov_b32 m0, s18
	s_nop 0
	buffer_load_dwordx4 v166, s[24:27], s53 offen lds
	s_nop 0
	s_mov_b32 m0, s19
	s_nop 0
	buffer_load_dwordx4 v167, s[24:27], s53 offen lds
	s_waitcnt vmcnt(8)
	s_waitcnt lgkmcnt(0)
	s_barrier
	s_setprio 0
	s_waitcnt lgkmcnt(7)
	v_mfma_f32_16x16x32_bf16 v[60:63], v[152:155], v[190:193], v[60:63]
	v_mfma_f32_16x16x32_bf16 v[52:55], v[160:163], v[190:193], v[52:55]
	s_waitcnt lgkmcnt(5)
	v_mfma_f32_16x16x32_bf16 v[44:47], v[152:155], v[198:201], v[44:47]
	v_mfma_f32_16x16x32_bf16 v[36:39], v[160:163], v[198:201], v[36:39]
	s_waitcnt lgkmcnt(3)
	v_mfma_f32_16x16x32_bf16 v[28:31], v[152:155], v[220:223], v[28:31]
	v_mfma_f32_16x16x32_bf16 v[20:23], v[160:163], v[220:223], v[20:23]
	s_waitcnt lgkmcnt(1)
	v_mfma_f32_16x16x32_bf16 v[12:15], v[152:155], v[228:231], v[12:15]
	v_mfma_f32_16x16x32_bf16 v[4:7], v[160:163], v[228:231], v[4:7]
	v_mfma_f32_16x16x32_bf16 v[60:63], v[156:159], v[194:197], v[60:63]
	v_mfma_f32_16x16x32_bf16 v[52:55], v[170:173], v[194:197], v[52:55]
	v_mfma_f32_16x16x32_bf16 v[44:47], v[156:159], v[202:205], v[44:47]
	v_mfma_f32_16x16x32_bf16 v[36:39], v[170:173], v[202:205], v[36:39]
	v_mfma_f32_16x16x32_bf16 v[28:31], v[156:159], v[224:227], v[28:31]
	v_mfma_f32_16x16x32_bf16 v[20:23], v[170:173], v[224:227], v[20:23]
	s_waitcnt lgkmcnt(0)
	v_mfma_f32_16x16x32_bf16 v[12:15], v[156:159], v[240:243], v[12:15]
	v_mfma_f32_16x16x32_bf16 v[4:7], v[170:173], v[240:243], v[4:7]
	s_setprio 1
	s_setprio 0
	v_mfma_f32_16x16x32_bf16 v[56:59], v[174:177], v[190:193], v[56:59]
	v_mfma_f32_16x16x32_bf16 v[48:51], v[182:185], v[190:193], v[48:51]
	v_mfma_f32_16x16x32_bf16 v[40:43], v[174:177], v[198:201], v[40:43]
	v_mfma_f32_16x16x32_bf16 v[32:35], v[182:185], v[198:201], v[32:35]
	v_mfma_f32_16x16x32_bf16 v[24:27], v[174:177], v[220:223], v[24:27]
	v_mfma_f32_16x16x32_bf16 v[16:19], v[182:185], v[220:223], v[16:19]
	v_mfma_f32_16x16x32_bf16 v[8:11], v[174:177], v[228:231], v[8:11]
	v_mfma_f32_16x16x32_bf16 v[0:3], v[182:185], v[228:231], v[0:3]
	v_mfma_f32_16x16x32_bf16 v[56:59], v[178:181], v[194:197], v[56:59]
	v_mfma_f32_16x16x32_bf16 v[48:51], v[186:189], v[194:197], v[48:51]
	v_mfma_f32_16x16x32_bf16 v[40:43], v[178:181], v[202:205], v[40:43]
	v_mfma_f32_16x16x32_bf16 v[32:35], v[186:189], v[202:205], v[32:35]
	v_mfma_f32_16x16x32_bf16 v[24:27], v[178:181], v[224:227], v[24:27]
	v_mfma_f32_16x16x32_bf16 v[16:19], v[186:189], v[224:227], v[16:19]
	v_mfma_f32_16x16x32_bf16 v[8:11], v[178:181], v[240:243], v[8:11]
	v_mfma_f32_16x16x32_bf16 v[0:3], v[186:189], v[240:243], v[0:3]
	s_setprio 1
	s_barrier
	s_add_i32 s52, s52, 2
	s_add_i32 s37, s37, 0x8000
	s_add_i32 s51, s51, 0x8000
	s_cmp_gt_u32 s52, 29
	s_cbranch_scc0 .LBB0_795

.Lnb_p6:
	s_add_i32 s11, s8, 0xffea4000
	s_cmpk_eq_i32 s10, 0x54
	s_cselect_b32 s13, s6, s11
	s_cselect_b32 s12, s7, s9
	s_or_b32 s11, s13, 0x4000
	s_mov_b32 m0, s87
	s_nop 0
	buffer_load_dwordx4 v220, s[20:23], s8 offen lds
	s_nop 0
	s_mov_b32 m0, s89
	s_nop 0
	buffer_load_dwordx4 v221, s[20:23], s8 offen lds
	s_waitcnt vmcnt(24)
	s_waitcnt lgkmcnt(0)
	s_barrier
	s_setprio 0
	s_waitcnt lgkmcnt(7)
	v_mfma_f32_16x16x32_bf16 v[164:167], v[128:131], v[184:187], 0
	v_mfma_f32_16x16x32_bf16 v[160:163], v[152:155], v[184:187], 0
	s_waitcnt lgkmcnt(5)
	v_mfma_f32_16x16x32_bf16 v[136:139], v[128:131], v[192:195], 0
	v_mfma_f32_16x16x32_bf16 v[132:135], v[152:155], v[192:195], 0
	s_waitcnt lgkmcnt(3)
	v_mfma_f32_16x16x32_bf16 v[116:119], v[128:131], v[200:203], 0
	v_mfma_f32_16x16x32_bf16 v[112:115], v[152:155], v[200:203], 0
	s_waitcnt lgkmcnt(1)
	v_mfma_f32_16x16x32_bf16 v[76:79], v[128:131], v[224:227], 0
	v_mfma_f32_16x16x32_bf16 v[72:75], v[152:155], v[224:227], 0
	v_mfma_f32_16x16x32_bf16 v[164:167], v[140:143], v[188:191], v[164:167]
	v_mfma_f32_16x16x32_bf16 v[160:163], v[156:159], v[188:191], v[160:163]
	v_mfma_f32_16x16x32_bf16 v[136:139], v[140:143], v[196:199], v[136:139]
	v_mfma_f32_16x16x32_bf16 v[132:135], v[156:159], v[196:199], v[132:135]
	v_mfma_f32_16x16x32_bf16 v[116:119], v[140:143], v[204:207], v[116:119]
	v_mfma_f32_16x16x32_bf16 v[112:115], v[156:159], v[204:207], v[112:115]
	s_waitcnt lgkmcnt(0)
	v_mfma_f32_16x16x32_bf16 v[76:79], v[140:143], v[228:231], v[76:79]
	v_mfma_f32_16x16x32_bf16 v[72:75], v[156:159], v[228:231], v[72:75]
	s_setprio 1
	s_setprio 0
	v_mfma_f32_16x16x32_bf16 v[148:151], v[168:171], v[184:187], 0
	v_mfma_f32_16x16x32_bf16 v[144:147], v[176:179], v[184:187], 0
	v_mfma_f32_16x16x32_bf16 v[124:127], v[168:171], v[192:195], 0
	v_mfma_f32_16x16x32_bf16 v[120:123], v[176:179], v[192:195], 0
	v_mfma_f32_16x16x32_bf16 v[108:111], v[168:171], v[200:203], 0
	v_mfma_f32_16x16x32_bf16 v[104:107], v[176:179], v[200:203], 0
	v_mfma_f32_16x16x32_bf16 v[68:71], v[168:171], v[224:227], 0
	v_mfma_f32_16x16x32_bf16 v[64:67], v[176:179], v[224:227], 0
	v_mfma_f32_16x16x32_bf16 v[148:151], v[172:175], v[188:191], v[148:151]
	v_mfma_f32_16x16x32_bf16 v[144:147], v[180:183], v[188:191], v[144:147]
	v_mfma_f32_16x16x32_bf16 v[124:127], v[172:175], v[196:199], v[124:127]
	v_mfma_f32_16x16x32_bf16 v[120:123], v[180:183], v[196:199], v[120:123]
	v_mfma_f32_16x16x32_bf16 v[108:111], v[172:175], v[204:207], v[108:111]
	v_mfma_f32_16x16x32_bf16 v[104:107], v[180:183], v[204:207], v[104:107]
	v_mfma_f32_16x16x32_bf16 v[68:71], v[172:175], v[228:231], v[68:71]
	v_mfma_f32_16x16x32_bf16 v[64:67], v[180:183], v[228:231], v[64:67]
	s_setprio 1
	s_barrier
	ds_read_b128 v[184:187], v223 offset:16384
	ds_read_b128 v[188:191], v223 offset:17408
	ds_read_b128 v[192:195], v223 offset:18432
	ds_read_b128 v[196:199], v223 offset:19456
	ds_read_b128 v[200:203], v223 offset:20480
	ds_read_b128 v[204:207], v223 offset:21504
	ds_read_b128 v[224:227], v223 offset:22528
	ds_read_b128 v[228:231], v223 offset:23552
	s_mov_b32 m0, s51
	s_nop 0
	buffer_load_dwordx4 v220, s[52:55], s12 offen lds
	s_add_i32 s14, s12, 0x160000
	s_mov_b32 m0, s74
	s_nop 0
	buffer_load_dwordx4 v221, s[52:55], s12 offen lds
	s_nop 0
	s_mov_b32 m0, s75
	s_nop 0
	buffer_load_dwordx4 v220, s[52:55], s14 offen lds
	s_nop 0
	s_mov_b32 m0, s76
	s_nop 0
	buffer_load_dwordx4 v221, s[52:55], s14 offen lds
	s_nop 0
	s_mov_b32 m0, s31
	s_nop 0
	buffer_load_dwordx4 v220, s[20:23], s13 offen lds
	s_nop 0
	s_mov_b32 m0, s77
	s_nop 0
	buffer_load_dwordx4 v221, s[20:23], s13 offen lds
	s_waitcnt vmcnt(24)
	s_waitcnt lgkmcnt(0)
	s_barrier
	s_setprio 0
	s_waitcnt lgkmcnt(7)
	v_mfma_f32_16x16x32_bf16 v[60:63], v[128:131], v[184:187], 0
	v_mfma_f32_16x16x32_bf16 v[56:59], v[152:155], v[184:187], 0
	s_waitcnt lgkmcnt(5)
	v_mfma_f32_16x16x32_bf16 v[44:47], v[128:131], v[192:195], 0
	v_mfma_f32_16x16x32_bf16 v[40:43], v[152:155], v[192:195], 0
	s_waitcnt lgkmcnt(3)
	v_mfma_f32_16x16x32_bf16 v[28:31], v[128:131], v[200:203], 0
	v_mfma_f32_16x16x32_bf16 v[24:27], v[152:155], v[200:203], 0
	s_waitcnt lgkmcnt(1)
	v_mfma_f32_16x16x32_bf16 v[12:15], v[128:131], v[224:227], 0
	v_mfma_f32_16x16x32_bf16 v[8:11], v[152:155], v[224:227], 0
	v_mfma_f32_16x16x32_bf16 v[60:63], v[140:143], v[188:191], v[60:63]
	v_mfma_f32_16x16x32_bf16 v[56:59], v[156:159], v[188:191], v[56:59]
	v_mfma_f32_16x16x32_bf16 v[44:47], v[140:143], v[196:199], v[44:47]
	v_mfma_f32_16x16x32_bf16 v[40:43], v[156:159], v[196:199], v[40:43]
	v_mfma_f32_16x16x32_bf16 v[28:31], v[140:143], v[204:207], v[28:31]
	v_mfma_f32_16x16x32_bf16 v[24:27], v[156:159], v[204:207], v[24:27]
	s_waitcnt lgkmcnt(0)
	v_mfma_f32_16x16x32_bf16 v[12:15], v[140:143], v[228:231], v[12:15]
	v_mfma_f32_16x16x32_bf16 v[8:11], v[156:159], v[228:231], v[8:11]
	s_setprio 1
	s_setprio 0
	v_mfma_f32_16x16x32_bf16 v[52:55], v[168:171], v[184:187], 0
	v_mfma_f32_16x16x32_bf16 v[48:51], v[176:179], v[184:187], 0
	v_mfma_f32_16x16x32_bf16 v[36:39], v[168:171], v[192:195], 0
	v_mfma_f32_16x16x32_bf16 v[32:35], v[176:179], v[192:195], 0
	v_mfma_f32_16x16x32_bf16 v[20:23], v[168:171], v[200:203], 0
	v_mfma_f32_16x16x32_bf16 v[16:19], v[176:179], v[200:203], 0
	v_mfma_f32_16x16x32_bf16 v[4:7], v[168:171], v[224:227], 0
	v_mfma_f32_16x16x32_bf16 v[0:3], v[176:179], v[224:227], 0
	v_mfma_f32_16x16x32_bf16 v[52:55], v[172:175], v[188:191], v[52:55]
	v_mfma_f32_16x16x32_bf16 v[48:51], v[180:183], v[188:191], v[48:51]
	v_mfma_f32_16x16x32_bf16 v[36:39], v[172:175], v[196:199], v[36:39]
	v_mfma_f32_16x16x32_bf16 v[32:35], v[180:183], v[196:199], v[32:35]
	v_mfma_f32_16x16x32_bf16 v[20:23], v[172:175], v[204:207], v[20:23]
	v_mfma_f32_16x16x32_bf16 v[16:19], v[180:183], v[204:207], v[16:19]
	v_mfma_f32_16x16x32_bf16 v[4:7], v[172:175], v[228:231], v[4:7]
	v_mfma_f32_16x16x32_bf16 v[0:3], v[180:183], v[228:231], v[0:3]
	s_setprio 1
	s_barrier
	v_add_u32_e32 v156, 0x18000, v222
	v_add_u32_e32 v180, 0x1c000, v222
	ds_read_b128 v[128:131], v156
	ds_read_b128 v[140:143], v156 offset:1024
	ds_read_b128 v[152:155], v156 offset:2048
	ds_read_b128 v[156:159], v156 offset:3072
	ds_read_b128 v[168:171], v180
	ds_read_b128 v[172:175], v180 offset:1024
	ds_read_b128 v[176:179], v180 offset:2048
	ds_read_b128 v[180:183], v180 offset:3072
	ds_read_b128 v[184:187], v223 offset:32768
	ds_read_b128 v[188:191], v223 offset:33792
	ds_read_b128 v[192:195], v223 offset:34816
	ds_read_b128 v[196:199], v223 offset:35840
	ds_read_b128 v[200:203], v223 offset:36864
	ds_read_b128 v[204:207], v223 offset:37888
	ds_read_b128 v[224:227], v223 offset:38912
	ds_read_b128 v[228:231], v223 offset:39936
	s_add_i32 s13, s13, 0x160000
	s_mov_b32 m0, s78
	s_nop 0
	buffer_load_dwordx4 v220, s[20:23], s13 offen lds
	s_nop 0
	s_mov_b32 m0, s79
	s_nop 0
	buffer_load_dwordx4 v221, s[20:23], s13 offen lds
	s_waitcnt vmcnt(8)
	s_waitcnt lgkmcnt(0)
	s_barrier
	s_setprio 0
	s_waitcnt lgkmcnt(7)
	v_mfma_f32_16x16x32_bf16 v[164:167], v[128:131], v[184:187], v[164:167]
	v_mfma_f32_16x16x32_bf16 v[160:163], v[152:155], v[184:187], v[160:163]
	s_waitcnt lgkmcnt(5)
	v_mfma_f32_16x16x32_bf16 v[136:139], v[128:131], v[192:195], v[136:139]
	v_mfma_f32_16x16x32_bf16 v[132:135], v[152:155], v[192:195], v[132:135]
	s_waitcnt lgkmcnt(3)
	v_mfma_f32_16x16x32_bf16 v[116:119], v[128:131], v[200:203], v[116:119]
	v_mfma_f32_16x16x32_bf16 v[112:115], v[152:155], v[200:203], v[112:115]
	s_waitcnt lgkmcnt(1)
	v_mfma_f32_16x16x32_bf16 v[76:79], v[128:131], v[224:227], v[76:79]
	v_mfma_f32_16x16x32_bf16 v[72:75], v[152:155], v[224:227], v[72:75]
	v_mfma_f32_16x16x32_bf16 v[164:167], v[140:143], v[188:191], v[164:167]
	v_mfma_f32_16x16x32_bf16 v[160:163], v[156:159], v[188:191], v[160:163]
	v_mfma_f32_16x16x32_bf16 v[136:139], v[140:143], v[196:199], v[136:139]
	v_mfma_f32_16x16x32_bf16 v[132:135], v[156:159], v[196:199], v[132:135]
	v_mfma_f32_16x16x32_bf16 v[116:119], v[140:143], v[204:207], v[116:119]
	v_mfma_f32_16x16x32_bf16 v[112:115], v[156:159], v[204:207], v[112:115]
	s_waitcnt lgkmcnt(0)
	v_mfma_f32_16x16x32_bf16 v[76:79], v[140:143], v[228:231], v[76:79]
	v_mfma_f32_16x16x32_bf16 v[72:75], v[156:159], v[228:231], v[72:75]
	s_setprio 1
	s_setprio 0
	v_mfma_f32_16x16x32_bf16 v[148:151], v[168:171], v[184:187], v[148:151]
	v_mfma_f32_16x16x32_bf16 v[144:147], v[176:179], v[184:187], v[144:147]
	v_mfma_f32_16x16x32_bf16 v[124:127], v[168:171], v[192:195], v[124:127]
	v_mfma_f32_16x16x32_bf16 v[120:123], v[176:179], v[192:195], v[120:123]
	v_mfma_f32_16x16x32_bf16 v[108:111], v[168:171], v[200:203], v[108:111]
	v_mfma_f32_16x16x32_bf16 v[104:107], v[176:179], v[200:203], v[104:107]
	v_mfma_f32_16x16x32_bf16 v[68:71], v[168:171], v[224:227], v[68:71]
	v_mfma_f32_16x16x32_bf16 v[64:67], v[176:179], v[224:227], v[64:67]
	v_mfma_f32_16x16x32_bf16 v[148:151], v[172:175], v[188:191], v[148:151]
	v_mfma_f32_16x16x32_bf16 v[144:147], v[180:183], v[188:191], v[144:147]
	v_mfma_f32_16x16x32_bf16 v[124:127], v[172:175], v[196:199], v[124:127]
	v_mfma_f32_16x16x32_bf16 v[120:123], v[180:183], v[196:199], v[120:123]
	v_mfma_f32_16x16x32_bf16 v[108:111], v[172:175], v[204:207], v[108:111]
	v_mfma_f32_16x16x32_bf16 v[104:107], v[180:183], v[204:207], v[104:107]
	v_mfma_f32_16x16x32_bf16 v[68:71], v[172:175], v[228:231], v[68:71]
	v_mfma_f32_16x16x32_bf16 v[64:67], v[180:183], v[228:231], v[64:67]
	s_setprio 1
	s_barrier
	ds_read_b128 v[184:187], v223 offset:49152
	ds_read_b128 v[188:191], v223 offset:50176
	ds_read_b128 v[192:195], v223 offset:51200
	ds_read_b128 v[196:199], v223 offset:52224
	ds_read_b128 v[200:203], v223 offset:53248
	ds_read_b128 v[204:207], v223 offset:54272
	ds_read_b128 v[224:227], v223 offset:55296
	ds_read_b128 v[228:231], v223 offset:56320
	s_or_b32 s13, s12, 0x4000
	s_mov_b32 m0, s34
	s_nop 0
	buffer_load_dwordx4 v220, s[52:55], s13 offen lds
	s_add_i32 s12, s12, 0x164000
	s_mov_b32 m0, s82
	s_nop 0
	buffer_load_dwordx4 v221, s[52:55], s13 offen lds
	s_nop 0
	s_mov_b32 m0, s85
	s_nop 0
	buffer_load_dwordx4 v220, s[52:55], s12 offen lds
	s_nop 0
	s_mov_b32 m0, s86
	s_nop 0
	buffer_load_dwordx4 v221, s[52:55], s12 offen lds
	s_nop 0
	s_mov_b32 m0, s83
	s_nop 0
	buffer_load_dwordx4 v220, s[20:23], s11 offen lds
	s_nop 0
	s_mov_b32 m0, s84
	s_nop 0
	buffer_load_dwordx4 v221, s[20:23], s11 offen lds
	s_waitcnt vmcnt(8)
	s_waitcnt lgkmcnt(0)
	s_barrier
	s_setprio 0
	s_waitcnt lgkmcnt(7)
	v_mfma_f32_16x16x32_bf16 v[60:63], v[128:131], v[184:187], v[60:63]
	v_mfma_f32_16x16x32_bf16 v[56:59], v[152:155], v[184:187], v[56:59]
	s_waitcnt lgkmcnt(5)
	v_mfma_f32_16x16x32_bf16 v[44:47], v[128:131], v[192:195], v[44:47]
	v_mfma_f32_16x16x32_bf16 v[40:43], v[152:155], v[192:195], v[40:43]
	s_waitcnt lgkmcnt(3)
	v_mfma_f32_16x16x32_bf16 v[28:31], v[128:131], v[200:203], v[28:31]
	v_mfma_f32_16x16x32_bf16 v[24:27], v[152:155], v[200:203], v[24:27]
	s_waitcnt lgkmcnt(1)
	v_mfma_f32_16x16x32_bf16 v[12:15], v[128:131], v[224:227], v[12:15]
	v_mfma_f32_16x16x32_bf16 v[8:11], v[152:155], v[224:227], v[8:11]
	v_mfma_f32_16x16x32_bf16 v[60:63], v[140:143], v[188:191], v[60:63]
	v_mfma_f32_16x16x32_bf16 v[56:59], v[156:159], v[188:191], v[56:59]
	v_mfma_f32_16x16x32_bf16 v[44:47], v[140:143], v[196:199], v[44:47]
	v_mfma_f32_16x16x32_bf16 v[40:43], v[156:159], v[196:199], v[40:43]
	v_mfma_f32_16x16x32_bf16 v[28:31], v[140:143], v[204:207], v[28:31]
	v_mfma_f32_16x16x32_bf16 v[24:27], v[156:159], v[204:207], v[24:27]
	s_waitcnt lgkmcnt(0)
	v_mfma_f32_16x16x32_bf16 v[12:15], v[140:143], v[228:231], v[12:15]
	v_mfma_f32_16x16x32_bf16 v[8:11], v[156:159], v[228:231], v[8:11]
	s_setprio 1
	s_setprio 0
	v_mfma_f32_16x16x32_bf16 v[52:55], v[168:171], v[184:187], v[52:55]
	v_mfma_f32_16x16x32_bf16 v[48:51], v[176:179], v[184:187], v[48:51]
	v_mfma_f32_16x16x32_bf16 v[36:39], v[168:171], v[192:195], v[36:39]
	v_mfma_f32_16x16x32_bf16 v[32:35], v[176:179], v[192:195], v[32:35]
	v_mfma_f32_16x16x32_bf16 v[20:23], v[168:171], v[200:203], v[20:23]
	v_mfma_f32_16x16x32_bf16 v[16:19], v[176:179], v[200:203], v[16:19]
	v_mfma_f32_16x16x32_bf16 v[4:7], v[168:171], v[224:227], v[4:7]
	v_mfma_f32_16x16x32_bf16 v[0:3], v[176:179], v[224:227], v[0:3]
	v_mfma_f32_16x16x32_bf16 v[52:55], v[172:175], v[188:191], v[52:55]
	v_mfma_f32_16x16x32_bf16 v[48:51], v[180:183], v[188:191], v[48:51]
	v_mfma_f32_16x16x32_bf16 v[36:39], v[172:175], v[196:199], v[36:39]
	v_mfma_f32_16x16x32_bf16 v[32:35], v[180:183], v[196:199], v[32:35]
	v_mfma_f32_16x16x32_bf16 v[20:23], v[172:175], v[204:207], v[20:23]
	v_mfma_f32_16x16x32_bf16 v[16:19], v[180:183], v[204:207], v[16:19]
	v_mfma_f32_16x16x32_bf16 v[4:7], v[172:175], v[228:231], v[4:7]
	v_mfma_f32_16x16x32_bf16 v[0:3], v[180:183], v[228:231], v[0:3]
	s_setprio 1
	s_barrier
	s_add_i32 s10, s10, 2
	s_add_i32 s8, s8, 0x8000
	s_add_i32 s9, s9, 0x8000
.LBB0_885:
	v_add_u32_e32 v156, 0x10000, v222
	v_add_u32_e32 v180, 0x14000, v222
	ds_read_b128 v[128:131], v156
	ds_read_b128 v[140:143], v156 offset:1024
	ds_read_b128 v[152:155], v156 offset:2048
	ds_read_b128 v[156:159], v156 offset:3072
	ds_read_b128 v[168:171], v180
	ds_read_b128 v[172:175], v180 offset:1024
	ds_read_b128 v[176:179], v180 offset:2048
	ds_read_b128 v[180:183], v180 offset:3072
	s_add_i32 s11, s8, 0xffea4000
	s_cmpk_eq_i32 s10, 0x54
	s_cselect_b32 s13, s6, s11
	s_cselect_b32 s12, s7, s9
	s_or_b32 s11, s13, 0x4000
	ds_read_b128 v[184:187], v223
	ds_read_b128 v[188:191], v223 offset:1024
	ds_read_b128 v[192:195], v223 offset:2048
	ds_read_b128 v[196:199], v223 offset:3072
	ds_read_b128 v[200:203], v223 offset:4096
	ds_read_b128 v[204:207], v223 offset:5120
	ds_read_b128 v[224:227], v223 offset:6144
	ds_read_b128 v[228:231], v223 offset:7168
	s_mov_b32 m0, s87
	s_nop 0
	buffer_load_dwordx4 v220, s[20:23], s8 offen lds
	s_nop 0
	s_mov_b32 m0, s89
	s_nop 0
	buffer_load_dwordx4 v221, s[20:23], s8 offen lds
	s_waitcnt vmcnt(8)
	s_waitcnt lgkmcnt(0)
	s_barrier
	s_setprio 0
	s_waitcnt lgkmcnt(7)
	v_mfma_f32_16x16x32_bf16 v[164:167], v[128:131], v[184:187], v[164:167]
	v_mfma_f32_16x16x32_bf16 v[160:163], v[152:155], v[184:187], v[160:163]
	s_waitcnt lgkmcnt(5)
	v_mfma_f32_16x16x32_bf16 v[136:139], v[128:131], v[192:195], v[136:139]
	v_mfma_f32_16x16x32_bf16 v[132:135], v[152:155], v[192:195], v[132:135]
	s_waitcnt lgkmcnt(3)
	v_mfma_f32_16x16x32_bf16 v[116:119], v[128:131], v[200:203], v[116:119]
	v_mfma_f32_16x16x32_bf16 v[112:115], v[152:155], v[200:203], v[112:115]
	s_waitcnt lgkmcnt(1)
	v_mfma_f32_16x16x32_bf16 v[76:79], v[128:131], v[224:227], v[76:79]
	v_mfma_f32_16x16x32_bf16 v[72:75], v[152:155], v[224:227], v[72:75]
	v_mfma_f32_16x16x32_bf16 v[164:167], v[140:143], v[188:191], v[164:167]
	v_mfma_f32_16x16x32_bf16 v[160:163], v[156:159], v[188:191], v[160:163]
	v_mfma_f32_16x16x32_bf16 v[136:139], v[140:143], v[196:199], v[136:139]
	v_mfma_f32_16x16x32_bf16 v[132:135], v[156:159], v[196:199], v[132:135]
	v_mfma_f32_16x16x32_bf16 v[116:119], v[140:143], v[204:207], v[116:119]
	v_mfma_f32_16x16x32_bf16 v[112:115], v[156:159], v[204:207], v[112:115]
	s_waitcnt lgkmcnt(0)
	v_mfma_f32_16x16x32_bf16 v[76:79], v[140:143], v[228:231], v[76:79]
	v_mfma_f32_16x16x32_bf16 v[72:75], v[156:159], v[228:231], v[72:75]
	s_setprio 1
	s_setprio 0
	v_mfma_f32_16x16x32_bf16 v[148:151], v[168:171], v[184:187], v[148:151]
	v_mfma_f32_16x16x32_bf16 v[144:147], v[176:179], v[184:187], v[144:147]
	v_mfma_f32_16x16x32_bf16 v[124:127], v[168:171], v[192:195], v[124:127]
	v_mfma_f32_16x16x32_bf16 v[120:123], v[176:179], v[192:195], v[120:123]
	v_mfma_f32_16x16x32_bf16 v[108:111], v[168:171], v[200:203], v[108:111]
	v_mfma_f32_16x16x32_bf16 v[104:107], v[176:179], v[200:203], v[104:107]
	v_mfma_f32_16x16x32_bf16 v[68:71], v[168:171], v[224:227], v[68:71]
	v_mfma_f32_16x16x32_bf16 v[64:67], v[176:179], v[224:227], v[64:67]
	v_mfma_f32_16x16x32_bf16 v[148:151], v[172:175], v[188:191], v[148:151]
	v_mfma_f32_16x16x32_bf16 v[144:147], v[180:183], v[188:191], v[144:147]
	v_mfma_f32_16x16x32_bf16 v[124:127], v[172:175], v[196:199], v[124:127]
	v_mfma_f32_16x16x32_bf16 v[120:123], v[180:183], v[196:199], v[120:123]
	v_mfma_f32_16x16x32_bf16 v[108:111], v[172:175], v[204:207], v[108:111]
	v_mfma_f32_16x16x32_bf16 v[104:107], v[180:183], v[204:207], v[104:107]
	v_mfma_f32_16x16x32_bf16 v[68:71], v[172:175], v[228:231], v[68:71]
	v_mfma_f32_16x16x32_bf16 v[64:67], v[180:183], v[228:231], v[64:67]
	s_setprio 1
	s_barrier
	ds_read_b128 v[184:187], v223 offset:16384
	ds_read_b128 v[188:191], v223 offset:17408
	ds_read_b128 v[192:195], v223 offset:18432
	ds_read_b128 v[196:199], v223 offset:19456
	ds_read_b128 v[200:203], v223 offset:20480
	ds_read_b128 v[204:207], v223 offset:21504
	ds_read_b128 v[224:227], v223 offset:22528
	ds_read_b128 v[228:231], v223 offset:23552
	s_mov_b32 m0, s51
	s_nop 0
	buffer_load_dwordx4 v220, s[52:55], s12 offen lds
	s_add_i32 s14, s12, 0x160000
	s_mov_b32 m0, s74
	s_nop 0
	buffer_load_dwordx4 v221, s[52:55], s12 offen lds
	s_nop 0
	s_mov_b32 m0, s75
	s_nop 0
	buffer_load_dwordx4 v220, s[52:55], s14 offen lds
	s_nop 0
	s_mov_b32 m0, s76
	s_nop 0
	buffer_load_dwordx4 v221, s[52:55], s14 offen lds
	s_nop 0
	s_mov_b32 m0, s31
	s_nop 0
	buffer_load_dwordx4 v220, s[20:23], s13 offen lds
	s_nop 0
	s_mov_b32 m0, s77
	s_nop 0
	buffer_load_dwordx4 v221, s[20:23], s13 offen lds
	s_waitcnt vmcnt(8)
	s_waitcnt lgkmcnt(0)
	s_barrier
	s_setprio 0
	s_waitcnt lgkmcnt(7)
	v_mfma_f32_16x16x32_bf16 v[60:63], v[128:131], v[184:187], v[60:63]
	v_mfma_f32_16x16x32_bf16 v[56:59], v[152:155], v[184:187], v[56:59]
	s_waitcnt lgkmcnt(5)
	v_mfma_f32_16x16x32_bf16 v[44:47], v[128:131], v[192:195], v[44:47]
	v_mfma_f32_16x16x32_bf16 v[40:43], v[152:155], v[192:195], v[40:43]
	s_waitcnt lgkmcnt(3)
	v_mfma_f32_16x16x32_bf16 v[28:31], v[128:131], v[200:203], v[28:31]
	v_mfma_f32_16x16x32_bf16 v[24:27], v[152:155], v[200:203], v[24:27]
	s_waitcnt lgkmcnt(1)
	v_mfma_f32_16x16x32_bf16 v[12:15], v[128:131], v[224:227], v[12:15]
	v_mfma_f32_16x16x32_bf16 v[8:11], v[152:155], v[224:227], v[8:11]
	v_mfma_f32_16x16x32_bf16 v[60:63], v[140:143], v[188:191], v[60:63]
	v_mfma_f32_16x16x32_bf16 v[56:59], v[156:159], v[188:191], v[56:59]
	v_mfma_f32_16x16x32_bf16 v[44:47], v[140:143], v[196:199], v[44:47]
	v_mfma_f32_16x16x32_bf16 v[40:43], v[156:159], v[196:199], v[40:43]
	v_mfma_f32_16x16x32_bf16 v[28:31], v[140:143], v[204:207], v[28:31]
	v_mfma_f32_16x16x32_bf16 v[24:27], v[156:159], v[204:207], v[24:27]
	s_waitcnt lgkmcnt(0)
	v_mfma_f32_16x16x32_bf16 v[12:15], v[140:143], v[228:231], v[12:15]
	v_mfma_f32_16x16x32_bf16 v[8:11], v[156:159], v[228:231], v[8:11]
	s_setprio 1
	s_setprio 0
	v_mfma_f32_16x16x32_bf16 v[52:55], v[168:171], v[184:187], v[52:55]
	v_mfma_f32_16x16x32_bf16 v[48:51], v[176:179], v[184:187], v[48:51]
	v_mfma_f32_16x16x32_bf16 v[36:39], v[168:171], v[192:195], v[36:39]
	v_mfma_f32_16x16x32_bf16 v[32:35], v[176:179], v[192:195], v[32:35]
	v_mfma_f32_16x16x32_bf16 v[20:23], v[168:171], v[200:203], v[20:23]
	v_mfma_f32_16x16x32_bf16 v[16:19], v[176:179], v[200:203], v[16:19]
	v_mfma_f32_16x16x32_bf16 v[4:7], v[168:171], v[224:227], v[4:7]
	v_mfma_f32_16x16x32_bf16 v[0:3], v[176:179], v[224:227], v[0:3]
	v_mfma_f32_16x16x32_bf16 v[52:55], v[172:175], v[188:191], v[52:55]
	v_mfma_f32_16x16x32_bf16 v[48:51], v[180:183], v[188:191], v[48:51]
	v_mfma_f32_16x16x32_bf16 v[36:39], v[172:175], v[196:199], v[36:39]
	v_mfma_f32_16x16x32_bf16 v[32:35], v[180:183], v[196:199], v[32:35]
	v_mfma_f32_16x16x32_bf16 v[20:23], v[172:175], v[204:207], v[20:23]
	v_mfma_f32_16x16x32_bf16 v[16:19], v[180:183], v[204:207], v[16:19]
	v_mfma_f32_16x16x32_bf16 v[4:7], v[172:175], v[228:231], v[4:7]
	v_mfma_f32_16x16x32_bf16 v[0:3], v[180:183], v[228:231], v[0:3]
	s_setprio 1
	s_barrier
	v_add_u32_e32 v156, 0x18000, v222
	v_add_u32_e32 v180, 0x1c000, v222
	ds_read_b128 v[128:131], v156
	ds_read_b128 v[140:143], v156 offset:1024
	ds_read_b128 v[152:155], v156 offset:2048
	ds_read_b128 v[156:159], v156 offset:3072
	ds_read_b128 v[168:171], v180
	ds_read_b128 v[172:175], v180 offset:1024
	ds_read_b128 v[176:179], v180 offset:2048
	ds_read_b128 v[180:183], v180 offset:3072
	ds_read_b128 v[184:187], v223 offset:32768
	ds_read_b128 v[188:191], v223 offset:33792
	ds_read_b128 v[192:195], v223 offset:34816
	ds_read_b128 v[196:199], v223 offset:35840
	ds_read_b128 v[200:203], v223 offset:36864
	ds_read_b128 v[204:207], v223 offset:37888
	ds_read_b128 v[224:227], v223 offset:38912
	ds_read_b128 v[228:231], v223 offset:39936
	s_add_i32 s13, s13, 0x160000
	s_mov_b32 m0, s78
	s_nop 0
	buffer_load_dwordx4 v220, s[20:23], s13 offen lds
	s_nop 0
	s_mov_b32 m0, s79
	s_nop 0
	buffer_load_dwordx4 v221, s[20:23], s13 offen lds
	s_waitcnt vmcnt(8)
	s_waitcnt lgkmcnt(0)
	s_barrier
	s_setprio 0
	s_waitcnt lgkmcnt(7)
	v_mfma_f32_16x16x32_bf16 v[164:167], v[128:131], v[184:187], v[164:167]
	v_mfma_f32_16x16x32_bf16 v[160:163], v[152:155], v[184:187], v[160:163]
	s_waitcnt lgkmcnt(5)
	v_mfma_f32_16x16x32_bf16 v[136:139], v[128:131], v[192:195], v[136:139]
	v_mfma_f32_16x16x32_bf16 v[132:135], v[152:155], v[192:195], v[132:135]
	s_waitcnt lgkmcnt(3)
	v_mfma_f32_16x16x32_bf16 v[116:119], v[128:131], v[200:203], v[116:119]
	v_mfma_f32_16x16x32_bf16 v[112:115], v[152:155], v[200:203], v[112:115]
	s_waitcnt lgkmcnt(1)
	v_mfma_f32_16x16x32_bf16 v[76:79], v[128:131], v[224:227], v[76:79]
	v_mfma_f32_16x16x32_bf16 v[72:75], v[152:155], v[224:227], v[72:75]
	v_mfma_f32_16x16x32_bf16 v[164:167], v[140:143], v[188:191], v[164:167]
	v_mfma_f32_16x16x32_bf16 v[160:163], v[156:159], v[188:191], v[160:163]
	v_mfma_f32_16x16x32_bf16 v[136:139], v[140:143], v[196:199], v[136:139]
	v_mfma_f32_16x16x32_bf16 v[132:135], v[156:159], v[196:199], v[132:135]
	v_mfma_f32_16x16x32_bf16 v[116:119], v[140:143], v[204:207], v[116:119]
	v_mfma_f32_16x16x32_bf16 v[112:115], v[156:159], v[204:207], v[112:115]
	s_waitcnt lgkmcnt(0)
	v_mfma_f32_16x16x32_bf16 v[76:79], v[140:143], v[228:231], v[76:79]
	v_mfma_f32_16x16x32_bf16 v[72:75], v[156:159], v[228:231], v[72:75]
	s_setprio 1
	s_setprio 0
	v_mfma_f32_16x16x32_bf16 v[148:151], v[168:171], v[184:187], v[148:151]
	v_mfma_f32_16x16x32_bf16 v[144:147], v[176:179], v[184:187], v[144:147]
	v_mfma_f32_16x16x32_bf16 v[124:127], v[168:171], v[192:195], v[124:127]
	v_mfma_f32_16x16x32_bf16 v[120:123], v[176:179], v[192:195], v[120:123]
	v_mfma_f32_16x16x32_bf16 v[108:111], v[168:171], v[200:203], v[108:111]
	v_mfma_f32_16x16x32_bf16 v[104:107], v[176:179], v[200:203], v[104:107]
	v_mfma_f32_16x16x32_bf16 v[68:71], v[168:171], v[224:227], v[68:71]
	v_mfma_f32_16x16x32_bf16 v[64:67], v[176:179], v[224:227], v[64:67]
	v_mfma_f32_16x16x32_bf16 v[148:151], v[172:175], v[188:191], v[148:151]
	v_mfma_f32_16x16x32_bf16 v[144:147], v[180:183], v[188:191], v[144:147]
	v_mfma_f32_16x16x32_bf16 v[124:127], v[172:175], v[196:199], v[124:127]
	v_mfma_f32_16x16x32_bf16 v[120:123], v[180:183], v[196:199], v[120:123]
	v_mfma_f32_16x16x32_bf16 v[108:111], v[172:175], v[204:207], v[108:111]
	v_mfma_f32_16x16x32_bf16 v[104:107], v[180:183], v[204:207], v[104:107]
	v_mfma_f32_16x16x32_bf16 v[68:71], v[172:175], v[228:231], v[68:71]
	v_mfma_f32_16x16x32_bf16 v[64:67], v[180:183], v[228:231], v[64:67]
	s_setprio 1
	s_barrier
	ds_read_b128 v[184:187], v223 offset:49152
	ds_read_b128 v[188:191], v223 offset:50176
	ds_read_b128 v[192:195], v223 offset:51200
	ds_read_b128 v[196:199], v223 offset:52224
	ds_read_b128 v[200:203], v223 offset:53248
	ds_read_b128 v[204:207], v223 offset:54272
	ds_read_b128 v[224:227], v223 offset:55296
	ds_read_b128 v[228:231], v223 offset:56320
	s_or_b32 s13, s12, 0x4000
	s_mov_b32 m0, s34
	s_nop 0
	buffer_load_dwordx4 v220, s[52:55], s13 offen lds
	s_add_i32 s12, s12, 0x164000
	s_mov_b32 m0, s82
	s_nop 0
	buffer_load_dwordx4 v221, s[52:55], s13 offen lds
	s_nop 0
	s_mov_b32 m0, s85
	s_nop 0
	buffer_load_dwordx4 v220, s[52:55], s12 offen lds
	s_nop 0
	s_mov_b32 m0, s86
	s_nop 0
	buffer_load_dwordx4 v221, s[52:55], s12 offen lds
	s_nop 0
	s_mov_b32 m0, s83
	s_nop 0
	buffer_load_dwordx4 v220, s[20:23], s11 offen lds
	s_nop 0
	s_mov_b32 m0, s84
	s_nop 0
	buffer_load_dwordx4 v221, s[20:23], s11 offen lds
	s_waitcnt vmcnt(8)
	s_waitcnt lgkmcnt(0)
	s_barrier
	s_setprio 0
	s_waitcnt lgkmcnt(7)
	v_mfma_f32_16x16x32_bf16 v[60:63], v[128:131], v[184:187], v[60:63]
	v_mfma_f32_16x16x32_bf16 v[56:59], v[152:155], v[184:187], v[56:59]
	s_waitcnt lgkmcnt(5)
	v_mfma_f32_16x16x32_bf16 v[44:47], v[128:131], v[192:195], v[44:47]
	v_mfma_f32_16x16x32_bf16 v[40:43], v[152:155], v[192:195], v[40:43]
	s_waitcnt lgkmcnt(3)
	v_mfma_f32_16x16x32_bf16 v[28:31], v[128:131], v[200:203], v[28:31]
	v_mfma_f32_16x16x32_bf16 v[24:27], v[152:155], v[200:203], v[24:27]
	s_waitcnt lgkmcnt(1)
	v_mfma_f32_16x16x32_bf16 v[12:15], v[128:131], v[224:227], v[12:15]
	v_mfma_f32_16x16x32_bf16 v[8:11], v[152:155], v[224:227], v[8:11]
	v_mfma_f32_16x16x32_bf16 v[60:63], v[140:143], v[188:191], v[60:63]
	v_mfma_f32_16x16x32_bf16 v[56:59], v[156:159], v[188:191], v[56:59]
	v_mfma_f32_16x16x32_bf16 v[44:47], v[140:143], v[196:199], v[44:47]
	v_mfma_f32_16x16x32_bf16 v[40:43], v[156:159], v[196:199], v[40:43]
	v_mfma_f32_16x16x32_bf16 v[28:31], v[140:143], v[204:207], v[28:31]
	v_mfma_f32_16x16x32_bf16 v[24:27], v[156:159], v[204:207], v[24:27]
	s_waitcnt lgkmcnt(0)
	v_mfma_f32_16x16x32_bf16 v[12:15], v[140:143], v[228:231], v[12:15]
	v_mfma_f32_16x16x32_bf16 v[8:11], v[156:159], v[228:231], v[8:11]
	s_setprio 1
	s_setprio 0
	v_mfma_f32_16x16x32_bf16 v[52:55], v[168:171], v[184:187], v[52:55]
	v_mfma_f32_16x16x32_bf16 v[48:51], v[176:179], v[184:187], v[48:51]
	v_mfma_f32_16x16x32_bf16 v[36:39], v[168:171], v[192:195], v[36:39]
	v_mfma_f32_16x16x32_bf16 v[32:35], v[176:179], v[192:195], v[32:35]
	v_mfma_f32_16x16x32_bf16 v[20:23], v[168:171], v[200:203], v[20:23]
	v_mfma_f32_16x16x32_bf16 v[16:19], v[176:179], v[200:203], v[16:19]
	v_mfma_f32_16x16x32_bf16 v[4:7], v[168:171], v[224:227], v[4:7]
	v_mfma_f32_16x16x32_bf16 v[0:3], v[176:179], v[224:227], v[0:3]
	v_mfma_f32_16x16x32_bf16 v[52:55], v[172:175], v[188:191], v[52:55]
	v_mfma_f32_16x16x32_bf16 v[48:51], v[180:183], v[188:191], v[48:51]
	v_mfma_f32_16x16x32_bf16 v[36:39], v[172:175], v[196:199], v[36:39]
	v_mfma_f32_16x16x32_bf16 v[32:35], v[180:183], v[196:199], v[32:35]
	v_mfma_f32_16x16x32_bf16 v[20:23], v[172:175], v[204:207], v[20:23]
	v_mfma_f32_16x16x32_bf16 v[16:19], v[180:183], v[204:207], v[16:19]
	v_mfma_f32_16x16x32_bf16 v[4:7], v[172:175], v[228:231], v[4:7]
	v_mfma_f32_16x16x32_bf16 v[0:3], v[180:183], v[228:231], v[0:3]
	s_setprio 1
	s_barrier
	s_add_i32 s10, s10, 2
	s_add_i32 s8, s8, 0x8000
	s_add_i32 s9, s9, 0x8000
	s_cmpk_gt_u32 s10, 0x55
	s_cbranch_scc0 .LBB0_885
